# non-temporal hint on more once-read streams: residual-stream loads of the fused epilogues, adaLN weight rows, first-norm input rows
# speedup vs baseline: 1.0229x; 1.0033x over previous
; __device__ __forceinline__ float silu_f(float x) { return x / (1.0f + __expf(-x)); }
; __device__ __forceinline__ void mod_phase(int j0, int j1, LAS unsigned char* lds, int vcu, int G, int tid, int wave, int lane) {
;     ...
;     for (int job = j0 + vcu; job < j1; job += G) {
;         const int lm = job / 144, colbase = (job % 144) * 64, kk = lane >> 4, c4 = lane & 15;
;         f32x4 acc0 = {0.f, 0.f, 0.f, 0.f}, acc1 = {0.f, 0.f, 0.f, 0.f};
;         const float* wp = w_ada + ((size_t)lm * 1024 + wave * 128 + kk) * 9216 + colbase + 4 * c4;
; #pragma unroll 8
;         for (int i = 0; i < 32; ++i) { const int k = wave * 128 + 4 * i + kk; const f32x4 wv = *(const f32x4*)(wp + (size_t)i * 4 * 9216); const float a0 = silu_f(c[k]), a1 = silu_f(c[1024 + k]); acc0 += a0 * wv; acc1 += a1 * wv; }
.LBB0_22:
	v_add_co_u32_e64 v4, s[8:9], s40, v40
	v_add_u32_e32 v34, s57, v66
	s_nop 0
	v_addc_co_u32_e64 v5, s[8:9], -1, v41, s[8:9]
	v_add_co_u32_e64 v6, s[8:9], s41, v40
	v_add_co_u32_e32 v28, vcc, 0xfff70000, v40
	s_nop 0
	v_addc_co_u32_e64 v7, s[8:9], -1, v41, s[8:9]
	v_add_co_u32_e64 v8, s[8:9], s52, v40
	v_addc_co_u32_e32 v29, vcc, -1, v41, vcc
	s_nop 0
	v_addc_co_u32_e64 v9, s[8:9], -1, v41, s[8:9]
	v_add_co_u32_e64 v30, s[8:9], s53, v40
	v_lshl_add_u64 v[72:73], v[34:35], 2, s[44:45]
	s_nop 0
	v_addc_co_u32_e64 v31, s[8:9], 0, v41, s[8:9]
	v_add_co_u32_e64 v68, s[8:9], s54, v40
	v_mov_b32_e32 v51, v35
	s_nop 0
	v_addc_co_u32_e64 v69, s[8:9], 0, v41, s[8:9]
	v_add_co_u32_e64 v70, s[8:9], s55, v40
	global_load_dwordx4 v[0:3], v[40:41], off nt
	global_load_dwordx4 v[16:19], v[8:9], off nt
	v_addc_co_u32_e64 v71, s[8:9], 0, v41, s[8:9]
	v_add_u32_e32 v50, 4, v34
	global_load_dwordx4 v[24:27], v[4:5], off nt
	global_load_dwordx4 v[20:23], v[6:7], off nt
	global_load_dwordx4 v[12:15], v[30:31], off nt
	global_load_dwordx4 v[8:11], v[68:69], off nt
	s_nop 0
	global_load_dwordx4 v[4:7], v[70:71], off nt
	v_add_co_u32_e32 v68, vcc, s33, v72
	v_add_u32_e32 v52, 8, v34
	v_add_u32_e32 v54, 12, v34
	v_add_u32_e32 v56, 16, v34
	v_add_u32_e32 v58, 20, v34
	v_add_u32_e32 v60, 24, v34
	v_add_u32_e32 v34, 28, v34
	v_addc_co_u32_e32 v69, vcc, 0, v73, vcc
	v_lshl_add_u64 v[50:51], v[50:51], 2, s[44:45]
	v_mov_b32_e32 v53, v35
	global_load_dwordx4 v[28:31], v[28:29], off nt
	v_lshl_add_u64 v[70:71], v[34:35], 2, s[44:45]
	global_load_dword v34, v[72:73], off
	global_load_dword v39, v[68:69], off
	global_load_dword v67, v[50:51], off
	v_add_co_u32_e32 v50, vcc, s33, v50
	v_lshl_add_u64 v[52:53], v[52:53], 2, s[44:45]
	s_nop 0
	v_addc_co_u32_e32 v51, vcc, 0, v51, vcc
	v_mov_b32_e32 v55, v35
	global_load_dword v72, v[52:53], off
	v_add_co_u32_e32 v52, vcc, s33, v52
	v_mov_b32_e32 v59, v35
	v_mov_b32_e32 v61, v35
	v_lshl_add_u64 v[54:55], v[54:55], 2, s[44:45]
	v_addc_co_u32_e32 v53, vcc, 0, v53, vcc
	v_mov_b32_e32 v57, v35
	v_lshl_add_u64 v[58:59], v[58:59], 2, s[44:45]
	v_lshl_add_u64 v[60:61], v[60:61], 2, s[44:45]
	global_load_dword v73, v[54:55], off
	global_load_dword v74, v[58:59], off
	global_load_dword v75, v[60:61], off
	global_load_dword v77, v[70:71], off
	v_add_co_u32_e32 v54, vcc, s33, v54
	v_lshl_add_u64 v[56:57], v[56:57], 2, s[44:45]
	s_nop 0
	v_addc_co_u32_e32 v55, vcc, 0, v55, vcc
	v_add_co_u32_e32 v68, vcc, s33, v56
	s_add_i32 s57, s57, 32
	s_nop 0
	v_addc_co_u32_e32 v69, vcc, 0, v57, vcc
	v_add_co_u32_e32 v58, vcc, s33, v58
	v_lshl_add_u64 v[40:41], v[40:41], 0, s[48:49]
	s_nop 0
	v_addc_co_u32_e32 v59, vcc, 0, v59, vcc
	v_add_co_u32_e32 v60, vcc, s33, v60
	s_cmpk_lg_i32 s57, 0x80
	s_nop 0
	v_addc_co_u32_e32 v61, vcc, 0, v61, vcc
	v_add_co_u32_e32 v70, vcc, s33, v70
	s_nop 1
	v_addc_co_u32_e32 v71, vcc, 0, v71, vcc
	global_load_dword v78, v[50:51], off
	global_load_dword v79, v[52:53], off
	global_load_dword v80, v[54:55], off
	global_load_dword v81, v[56:57], off
	global_load_dword v82, v[68:69], off
	global_load_dword v83, v[58:59], off
	global_load_dword v84, v[60:61], off
	global_load_dword v85, v[70:71], off
	s_waitcnt vmcnt(15)
	v_mul_f32_e32 v50, 0xbfb8aa3b, v34
	v_exp_f32_e32 v50, v50
	s_waitcnt vmcnt(14)
	v_mul_f32_e32 v51, 0xbfb8aa3b, v39
	s_waitcnt vmcnt(13)
	v_mul_f32_e32 v52, 0xbfb8aa3b, v67
	v_exp_f32_e32 v51, v51
	v_exp_f32_e32 v52, v52
	v_add_f32_e32 v50, 1.0, v50
	v_div_scale_f32 v86, s[8:9], v50, v50, v34
	s_waitcnt vmcnt(12)
	v_mul_f32_e32 v53, 0xbfb8aa3b, v72
	v_exp_f32_e32 v53, v53
	v_add_f32_e32 v51, 1.0, v51
	v_add_f32_e32 v52, 1.0, v52
	v_rcp_f32_e32 v88, v86
	v_div_scale_f32 v89, s[8:9], v51, v51, v39
	v_div_scale_f32 v91, s[8:9], v52, v52, v67
	s_waitcnt vmcnt(11)
	v_mul_f32_e32 v54, 0xbfb8aa3b, v73
	s_waitcnt vmcnt(9)
	v_mul_f32_e32 v56, 0xbfb8aa3b, v75
	s_waitcnt vmcnt(8)
	v_mul_f32_e32 v57, 0xbfb8aa3b, v77
	v_exp_f32_e32 v56, v56
	v_exp_f32_e32 v57, v57
	v_exp_f32_e32 v54, v54
	v_rcp_f32_e32 v103, v89
	v_add_f32_e32 v56, 1.0, v56
	v_add_f32_e32 v57, 1.0, v57
	v_div_scale_f32 v99, s[8:9], v56, v56, v75
	v_add_f32_e32 v53, 1.0, v53
	v_div_scale_f32 v101, s[8:9], v57, v57, v77
	v_rcp_f32_e32 v104, v91
	v_rcp_f32_e32 v120, v99
	v_mul_f32_e32 v55, 0xbfb8aa3b, v74
	v_div_scale_f32 v93, s[8:9], v53, v53, v72
	v_rcp_f32_e32 v123, v101
	v_exp_f32_e32 v55, v55
	s_waitcnt vmcnt(7)
	v_mul_f32_e32 v58, 0xbfb8aa3b, v78
	v_exp_f32_e32 v58, v58
	s_waitcnt vmcnt(6)
	v_mul_f32_e32 v59, 0xbfb8aa3b, v79
	v_exp_f32_e32 v59, v59
	s_waitcnt vmcnt(3)
	v_mul_f32_e32 v68, 0xbfb8aa3b, v82
	v_exp_f32_e32 v68, v68
	s_waitcnt vmcnt(1)
	v_mul_f32_e32 v70, 0xbfb8aa3b, v84
	s_waitcnt vmcnt(0)
; __device__ __forceinline__ float silu_f(float x) { return x / (1.0f + __expf(-x)); }
; __device__ __forceinline__ void mod_phase(int j0, int j1, LAS unsigned char* lds, int vcu, int G, int tid, int wave, int lane) {
;     ...
;         for (int i = 0; i < 32; ++i) { const int k = wave * 128 + 4 * i + kk; const f32x4 wv = *(const f32x4*)(wp + (size_t)i * 4 * 9216); const float a0 = silu_f(c[k]), a1 = silu_f(c[1024 + k]); acc0 += a0 * wv; acc1 += a1 * wv; }
	v_mul_f32_e32 v71, 0xbfb8aa3b, v85
	v_exp_f32_e32 v70, v70
	v_exp_f32_e32 v71, v71
	v_mul_f32_e32 v60, 0xbfb8aa3b, v80
	v_mul_f32_e32 v61, 0xbfb8aa3b, v81
	v_exp_f32_e32 v60, v60
	v_add_f32_e32 v58, 1.0, v58
	v_add_f32_e32 v70, 1.0, v70
	v_exp_f32_e32 v61, v61
	v_add_f32_e32 v68, 1.0, v68
	v_add_f32_e32 v71, 1.0, v71
	v_div_scale_f32 v105, s[14:15], v58, v58, v78
	v_div_scale_f32 v121, s[14:15], v70, v70, v84
	v_add_f32_e32 v59, 1.0, v59
	v_div_scale_f32 v115, s[14:15], v68, v68, v82
	v_div_scale_f32 v124, s[14:15], v71, v71, v85
	v_rcp_f32_e32 v126, v105
	v_rcp_f32_e32 v132, v121
	v_mul_f32_e32 v69, 0xbfb8aa3b, v83
	v_add_f32_e32 v54, 1.0, v54
	v_rcp_f32_e32 v107, v93
	v_div_scale_f32 v108, s[14:15], v59, v59, v79
	v_rcp_f32_e32 v130, v115
	v_rcp_f32_e32 v133, v124
	v_fma_f32 v134, -v86, v88, 1.0
	v_exp_f32_e32 v69, v69
	v_div_scale_f32 v87, vcc, v34, v50, v34
	v_div_scale_f32 v95, s[8:9], v54, v54, v73
	v_add_f32_e32 v60, 1.0, v60
	v_rcp_f32_e32 v127, v108
	v_fmac_f32_e32 v88, v134, v88
	v_fma_f32 v134, -v89, v103, 1.0
	v_div_scale_f32 v90, s[36:37], v39, v51, v39
	v_add_f32_e32 v61, 1.0, v61
	v_rcp_f32_e32 v110, v95
	v_div_scale_f32 v111, s[14:15], v60, v60, v80
	v_fma_f32 v135, -v91, v104, 1.0
	v_fma_f32 v139, -v99, v120, 1.0
	v_mul_f32_e32 v141, v87, v88
	v_fmac_f32_e32 v103, v134, v103
	v_div_scale_f32 v92, s[26:27], v67, v52, v67
	v_div_scale_f32 v113, s[14:15], v61, v61, v81
	v_rcp_f32_e32 v128, v111
	v_fma_f32 v140, -v101, v123, 1.0
	v_fmac_f32_e32 v104, v135, v104
	v_fma_f32 v134, -v105, v126, 1.0
	v_fmac_f32_e32 v120, v139, v120
	v_fma_f32 v139, -v121, v132, 1.0
	v_fma_f32 v143, -v86, v141, v87
	v_mul_f32_e32 v144, v90, v103
	v_add_f32_e32 v55, 1.0, v55
	v_div_scale_f32 v106, s[38:39], v78, v58, v78
	v_rcp_f32_e32 v129, v113
	v_fma_f32 v136, -v93, v107, 1.0
	v_fma_f32 v142, -v115, v130, 1.0
	v_fmac_f32_e32 v123, v140, v123
	v_fma_f32 v140, -v124, v133, 1.0
	v_mul_f32_e32 v145, v92, v104
	v_fmac_f32_e32 v126, v134, v126
	v_fmac_f32_e32 v132, v139, v132
	v_fmac_f32_e32 v141, v143, v88
	v_fma_f32 v139, -v89, v144, v90
	v_div_scale_f32 v94, s[22:23], v72, v53, v72
	v_div_scale_f32 v97, s[8:9], v55, v55, v74
	v_add_f32_e32 v69, 1.0, v69
	v_fmac_f32_e32 v107, v136, v107
	v_fma_f32 v135, -v108, v127, 1.0
	v_fmac_f32_e32 v130, v142, v130
	v_fmac_f32_e32 v133, v140, v133
	v_fma_f32 v140, -v91, v145, v92
	v_mul_f32_e32 v142, v106, v126
	v_fma_f32 v86, -v86, v141, v87
	v_fmac_f32_e32 v144, v139, v103
	v_div_scale_f32 v109, s[34:35], v79, v59, v79
	v_rcp_f32_e32 v117, v97
	v_div_scale_f32 v118, s[14:15], v69, v69, v83
	v_fma_f32 v137, -v95, v110, 1.0
	v_mul_f32_e32 v134, v94, v107
	v_fmac_f32_e32 v127, v135, v127
	v_fmac_f32_e32 v145, v140, v104
	v_fma_f32 v87, -v105, v142, v106
	v_div_fmas_f32 v86, v86, v88, v141
	v_fma_f32 v88, -v89, v144, v90
	s_mov_b64 vcc, s[36:37]
	v_div_scale_f32 v96, s[18:19], v73, v54, v73
	v_rcp_f32_e32 v131, v118
	v_fmac_f32_e32 v110, v137, v110
	v_fma_f32 v136, -v111, v128, 1.0
	v_fma_f32 v143, -v93, v134, v94
	v_mul_f32_e32 v146, v109, v127
	v_fma_f32 v89, -v91, v145, v92
	v_fmac_f32_e32 v142, v87, v126
	v_div_fmas_f32 v88, v88, v103, v144
	v_div_fixup_f32 v34, v86, v50, v34
	s_mov_b64 vcc, s[26:27]
	v_div_scale_f32 v112, s[30:31], v80, v60, v80
	v_fma_f32 v137, -v113, v129, 1.0
	v_mul_f32_e32 v135, v96, v110
	v_fmac_f32_e32 v128, v136, v128
	v_fmac_f32_e32 v134, v143, v107
	v_fma_f32 v139, -v108, v146, v109
	v_fma_f32 v50, -v105, v142, v106
	v_pk_fma_f32 v[48:49], v[28:29], v[34:35], v[48:49] op_sel_hi:[1,0,1]
	v_pk_fma_f32 v[44:45], v[30:31], v[34:35], v[44:45] op_sel_hi:[1,0,1]
	v_div_fixup_f32 v34, v88, v51, v39
	v_div_fmas_f32 v39, v89, v104, v145
	s_mov_b64 vcc, s[38:39]
	v_div_scale_f32 v114, s[28:29], v81, v61, v81
	v_fmac_f32_e32 v129, v137, v129
	v_fma_f32 v147, -v95, v135, v96
	v_mul_f32_e32 v148, v112, v128
	v_fma_f32 v87, -v93, v134, v94
	v_fmac_f32_e32 v146, v139, v127
	v_pk_fma_f32 v[28:29], v[28:29], v[34:35], v[46:47] op_sel_hi:[1,0,1]
	v_pk_fma_f32 v[30:31], v[30:31], v[34:35], v[42:43] op_sel_hi:[1,0,1]
	v_div_fmas_f32 v46, v50, v126, v142
	v_div_fixup_f32 v34, v39, v52, v67
	s_mov_b64 vcc, s[22:23]
	v_div_scale_f32 v116, s[24:25], v82, v68, v82
	v_fma_f32 v138, -v97, v117, 1.0
	v_mul_f32_e32 v149, v114, v129
	v_fmac_f32_e32 v135, v147, v110
	v_fma_f32 v140, -v111, v148, v112
	v_fma_f32 v86, -v108, v146, v109
	v_pk_fma_f32 v[42:43], v[26:27], v[34:35], v[44:45] op_sel_hi:[1,0,1]
	v_pk_fma_f32 v[44:45], v[24:25], v[34:35], v[48:49] op_sel_hi:[1,0,1]
	v_div_fixup_f32 v34, v46, v58, v78
	v_div_fmas_f32 v39, v87, v107, v134
	s_mov_b64 vcc, s[34:35]
	v_div_scale_f32 v98, s[12:13], v74, v55, v74
	v_fmac_f32_e32 v117, v138, v117
	v_fma_f32 v138, -v118, v131, 1.0
	v_mul_f32_e32 v150, v116, v130
	v_fma_f32 v143, -v113, v149, v114
	v_fma_f32 v90, -v95, v135, v96
	v_fmac_f32_e32 v148, v140, v128
	v_pk_fma_f32 v[26:27], v[26:27], v[34:35], v[30:31] op_sel_hi:[1,0,1]
	v_pk_fma_f32 v[24:25], v[24:25], v[34:35], v[28:29] op_sel_hi:[1,0,1]
	v_div_fmas_f32 v34, v86, v127, v146
	s_mov_b64 vcc, s[18:19]
; #define LAS __attribute__((address_space(3)))
; __device__ __forceinline__ float silu_f(float x) { return x / (1.0f + __expf(-x)); }
; __device__ __forceinline__ void mod_phase(int j0, int j1, LAS unsigned char* lds, int vcu, int G, int tid, int wave, int lane) {
;     ...
;         for (int i = 0; i < 32; ++i) { const int k = wave * 128 + 4 * i + kk; const f32x4 wv = *(const f32x4*)(wp + (size_t)i * 4 * 9216); const float a0 = silu_f(c[k]), a1 = silu_f(c[1024 + k]); acc0 += a0 * wv; acc1 += a1 * wv; }
; #pragma unroll
;         for (int e = 0; e < 4; ++e) { acc0[e] += __shfl_xor(acc0[e], 16); acc0[e] += __shfl_xor(acc0[e], 32); acc1[e] += __shfl_xor(acc1[e], 16); acc1[e] += __shfl_xor(acc1[e], 32); }
;         if (kk == 0) { *(LAS f32x4*)(part + (wave * 2 + 0) * 64 + 4 * c4) = acc0; *(LAS f32x4*)(part + (wave * 2 + 1) * 64 + 4 * c4) = acc1; }
	v_div_scale_f32 v119, s[20:21], v83, v69, v83
	v_mul_f32_e32 v136, v98, v117
	v_fmac_f32_e32 v131, v138, v131
	v_fma_f32 v147, -v115, v150, v116
	v_fmac_f32_e32 v149, v143, v129
	v_fma_f32 v94, -v111, v148, v112
	v_div_fixup_f32 v28, v39, v53, v72
	v_div_fixup_f32 v34, v34, v59, v79
	v_div_fmas_f32 v39, v90, v110, v135
	s_mov_b64 vcc, s[30:31]
	v_div_scale_f32 v100, s[10:11], v75, v56, v75
	v_fma_f32 v151, -v97, v136, v98
	v_mul_f32_e32 v152, v119, v131
	v_fmac_f32_e32 v150, v147, v130
	v_fma_f32 v95, -v113, v149, v114
	v_pk_fma_f32 v[30:31], v[20:21], v[28:29], v[44:45] op_sel_hi:[1,0,1]
	v_pk_fma_f32 v[28:29], v[22:23], v[28:29], v[42:43] op_sel_hi:[1,0,1]
	v_pk_fma_f32 v[20:21], v[20:21], v[34:35], v[24:25] op_sel_hi:[1,0,1]
	v_pk_fma_f32 v[22:23], v[22:23], v[34:35], v[26:27] op_sel_hi:[1,0,1]
	v_div_fmas_f32 v34, v94, v128, v148
	v_div_fixup_f32 v24, v39, v54, v73
	s_mov_b64 vcc, s[28:29]
	v_div_scale_f32 v122, s[16:17], v84, v70, v84
	v_mul_f32_e32 v137, v100, v120
	v_fmac_f32_e32 v136, v151, v117
	v_fma_f32 v151, -v118, v152, v119
	v_fma_f32 v96, -v115, v150, v116
	v_pk_fma_f32 v[26:27], v[18:19], v[24:25], v[28:29] op_sel_hi:[1,0,1]
	v_div_fixup_f32 v28, v34, v60, v80
	v_div_fmas_f32 v29, v95, v129, v149
	s_mov_b64 vcc, s[24:25]
	v_div_scale_f32 v102, s[8:9], v77, v57, v77
	v_fma_f32 v153, -v99, v137, v100
	v_mul_f32_e32 v155, v122, v132
	v_fma_f32 v91, -v97, v136, v98
	v_fmac_f32_e32 v152, v151, v131
	v_pk_fma_f32 v[24:25], v[16:17], v[24:25], v[30:31] op_sel_hi:[1,0,1]
	v_pk_fma_f32 v[18:19], v[18:19], v[28:29], v[22:23] op_sel_hi:[1,0,1]
	v_pk_fma_f32 v[16:17], v[16:17], v[28:29], v[20:21] op_sel_hi:[1,0,1]
	v_div_fixup_f32 v20, v29, v61, v81
	v_div_fmas_f32 v28, v96, v130, v150
	s_mov_b64 vcc, s[12:13]
	v_div_scale_f32 v125, s[14:15], v85, v71, v85
	v_mul_f32_e32 v138, v102, v123
	v_fmac_f32_e32 v137, v153, v120
	v_fma_f32 v153, -v121, v155, v122
	v_fma_f32 v97, -v118, v152, v119
	v_pk_fma_f32 v[22:23], v[0:1], v[20:21], v[24:25] op_sel_hi:[1,0,1]
	v_div_fmas_f32 v25, v91, v117, v136
	v_div_fixup_f32 v24, v28, v68, v82
	s_mov_b64 vcc, s[20:21]
	v_fma_f32 v154, -v101, v138, v102
	v_mul_f32_e32 v156, v125, v133
	v_fma_f32 v92, -v99, v137, v100
	v_fmac_f32_e32 v155, v153, v132
	v_pk_fma_f32 v[0:1], v[0:1], v[24:25], v[16:17] op_sel_hi:[1,0,1]
	v_div_fmas_f32 v17, v97, v131, v152
	s_mov_b64 vcc, s[10:11]
	v_fmac_f32_e32 v138, v154, v123
	v_fma_f32 v154, -v124, v156, v125
	v_fma_f32 v98, -v121, v155, v122
	v_pk_fma_f32 v[20:21], v[2:3], v[20:21], v[26:27] op_sel_hi:[1,0,1]
	v_pk_fma_f32 v[2:3], v[2:3], v[24:25], v[18:19] op_sel_hi:[1,0,1]
	v_div_fixup_f32 v16, v25, v55, v74
	v_div_fixup_f32 v18, v17, v69, v83
	v_div_fmas_f32 v19, v92, v120, v137
	s_mov_b64 vcc, s[16:17]
	v_fma_f32 v93, -v101, v138, v102
	v_fmac_f32_e32 v156, v154, v133
	v_pk_fma_f32 v[20:21], v[14:15], v[16:17], v[20:21] op_sel_hi:[1,0,1]
	v_pk_fma_f32 v[16:17], v[12:13], v[16:17], v[22:23] op_sel_hi:[1,0,1]
	v_pk_fma_f32 v[0:1], v[12:13], v[18:19], v[0:1] op_sel_hi:[1,0,1]
	v_div_fmas_f32 v13, v98, v132, v155
	s_mov_b64 vcc, s[8:9]
	v_fma_f32 v99, -v124, v156, v125
	v_pk_fma_f32 v[2:3], v[14:15], v[18:19], v[2:3] op_sel_hi:[1,0,1]
	v_div_fixup_f32 v12, v19, v56, v75
	v_div_fixup_f32 v14, v13, v70, v84
	v_div_fmas_f32 v15, v93, v123, v138
	s_mov_b64 vcc, s[14:15]
	v_pk_fma_f32 v[16:17], v[8:9], v[12:13], v[16:17] op_sel_hi:[1,0,1]
	v_pk_fma_f32 v[0:1], v[8:9], v[14:15], v[0:1] op_sel_hi:[1,0,1]
	v_div_fmas_f32 v9, v99, v133, v156
	v_pk_fma_f32 v[12:13], v[10:11], v[12:13], v[20:21] op_sel_hi:[1,0,1]
	v_pk_fma_f32 v[2:3], v[10:11], v[14:15], v[2:3] op_sel_hi:[1,0,1]
	v_div_fixup_f32 v8, v15, v57, v77
	v_div_fixup_f32 v10, v9, v71, v85
	v_pk_fma_f32 v[44:45], v[6:7], v[8:9], v[12:13] op_sel_hi:[1,0,1]
	v_pk_fma_f32 v[48:49], v[4:5], v[8:9], v[16:17] op_sel_hi:[1,0,1]
	v_pk_fma_f32 v[42:43], v[6:7], v[10:11], v[2:3] op_sel_hi:[1,0,1]
	v_pk_fma_f32 v[46:47], v[4:5], v[10:11], v[0:1] op_sel_hi:[1,0,1]
	s_cbranch_scc1 .LBB0_22
	ds_bpermute_b32 v0, v33, v48
	ds_bpermute_b32 v1, v33, v49
	ds_bpermute_b32 v4, v33, v46
	ds_bpermute_b32 v5, v33, v47
	ds_bpermute_b32 v8, v33, v44
	ds_bpermute_b32 v9, v33, v45
	ds_bpermute_b32 v12, v33, v42
	ds_bpermute_b32 v13, v33, v43
	s_waitcnt lgkmcnt(6)
	v_pk_add_f32 v[0:1], v[48:49], v[0:1]
	s_waitcnt lgkmcnt(4)
	v_pk_add_f32 v[4:5], v[46:47], v[4:5]
	s_waitcnt lgkmcnt(2)
	v_pk_add_f32 v[8:9], v[44:45], v[8:9]
	ds_bpermute_b32 v2, v62, v0
	s_waitcnt lgkmcnt(1)
	v_pk_add_f32 v[12:13], v[42:43], v[12:13]
	ds_bpermute_b32 v3, v62, v1
	ds_bpermute_b32 v6, v62, v4
	ds_bpermute_b32 v7, v62, v5
	ds_bpermute_b32 v10, v62, v8
	ds_bpermute_b32 v11, v62, v9
	ds_bpermute_b32 v14, v62, v12
	ds_bpermute_b32 v15, v62, v13
	s_and_saveexec_b64 s[8:9], s[4:5]
	s_cbranch_execz .LBB0_25
	s_waitcnt lgkmcnt(0)
	v_pk_add_f32 v[14:15], v[12:13], v[14:15]
	v_pk_add_f32 v[12:13], v[4:5], v[6:7]
	v_pk_add_f32 v[4:5], v[8:9], v[10:11]
	v_pk_add_f32 v[2:3], v[0:1], v[2:3]
	ds_write_b128 v63, v[2:5]
	ds_write_b128 v63, v[12:15] offset:256

; __device__ __forceinline__ unsigned pk2(float lo, float hi) { return f2bf(lo) | (f2bf(hi) << 16); }
; template <bool MIX>
; __device__ __forceinline__ void norm_phase(const float* xin, int l, int sub, LAS unsigned char* lds, int vcu, int G, int tid, int wave, int lane) {
;     ...
;         for (int i = 0; i < 8; ++i) { const int rl = wave * 8 + i, row = blk * 64 + rl;
;             const f32x4* xr = (const f32x4*)(xin + (size_t)row * 1024) + lane;
;             f32x4 v[4]; float ss = 0.f;
; #pragma unroll
;             for (int j = 0; j < 4; ++j) { v[j] = xr[64 * j]; ss += (v[j].x * v[j].x + v[j].y * v[j].y) + (v[j].z * v[j].z + v[j].w * v[j].w); }
;             const float rstd = 1.0f / sqrtf(wave_sum(ss) * (1.0f / 1024.0f) + 1e-6f);
;             unsigned long long* o8 = (unsigned long long*)(XN + (size_t)row * 1024) + lane;
; #pragma unroll
;             for (int j = 0; j < 4; ++j) { const f32x4 g = ((const f32x4*)gain)[64 * j + lane], sc = ((const f32x4*)(scale + b * 9216))[64 * j + lane], sh = ((const f32x4*)(shift + b * 9216))[64 * j + lane];
;                 v[j] = (v[j] * rstd * g) * (1.0f + sc) + sh;
;                 o8[64 * j] = (unsigned long long)pk2(v[j].x, v[j].y) | ((unsigned long long)pk2(v[j].z, v[j].w) << 32); }
.LBB0_83:
	s_add_i32 s4, s3, s20
	s_ashr_i32 s5, s4, 31
	s_lshl_b64 s[12:13], s[4:5], 12
	v_lshl_add_u64 v[26:27], v[12:13], 0, s[12:13]
	global_load_dwordx4 v[0:3], v[16:17], off
	global_load_dwordx4 v[8:11], v[22:23], off
	global_load_dwordx4 v[4:7], v[24:25], off
	global_load_dwordx4 v[46:49], v[26:27], off nt
	global_load_dwordx4 v[50:53], v[26:27], off offset:1024 nt
	global_load_dwordx4 v[54:57], v[26:27], off offset:3072 nt
	global_load_dwordx4 v[58:61], v[26:27], off offset:2048 nt
	s_add_i32 s6, s4, 1
	s_add_i32 s8, s4, 2
	s_add_i32 s10, s4, 3
	s_lshl_b64 s[4:5], s[4:5], 11
	s_ashr_i32 s7, s6, 31
	v_lshl_add_u64 v[36:37], v[14:15], 0, s[4:5]
	s_lshl_b64 s[4:5], s[6:7], 12
	v_lshl_add_u64 v[62:63], v[12:13], 0, s[4:5]
	s_lshl_b64 s[6:7], s[6:7], 11
	v_lshl_add_u64 v[34:35], v[14:15], 0, s[6:7]
	s_ashr_i32 s9, s8, 31
	s_lshl_b64 s[12:13], s[8:9], 12
	v_lshl_add_u64 v[32:33], v[12:13], 0, s[12:13]
	s_lshl_b64 s[8:9], s[8:9], 11
	v_lshl_add_u64 v[30:31], v[14:15], 0, s[8:9]
	s_ashr_i32 s11, s10, 31
	s_lshl_b64 s[14:15], s[10:11], 12
	v_lshl_add_u64 v[28:29], v[12:13], 0, s[14:15]
	s_lshl_b64 s[10:11], s[10:11], 11
	v_lshl_add_u64 v[26:27], v[14:15], 0, s[10:11]
	s_add_i32 s20, s20, 4
	s_cmp_eq_u32 s20, 8
	s_waitcnt vmcnt(3)
	v_pk_mul_f32 v[64:65], v[48:49], v[48:49]
	v_pk_mul_f32 v[66:67], v[46:47], v[46:47]
	s_waitcnt vmcnt(2)
	v_pk_mul_f32 v[68:69], v[52:53], v[52:53]
	v_pk_mul_f32 v[70:71], v[50:51], v[50:51]
	v_pk_mov_b32 v[78:79], v[66:67], v[64:65] op_sel:[1,0]
	v_mov_b32_e32 v67, v65
	v_pk_mov_b32 v[64:65], v[70:71], v[68:69] op_sel:[1,0]
	v_mov_b32_e32 v71, v69
	s_waitcnt vmcnt(1)
	v_mul_f32_e32 v75, v56, v56
	s_waitcnt vmcnt(0)
	v_mul_f32_e32 v72, v59, v59
	v_mul_f32_e32 v74, v61, v61
	v_pk_add_f32 v[66:67], v[78:79], v[66:67]
	v_pk_add_f32 v[64:65], v[64:65], v[70:71]
	v_mul_f32_e32 v77, v57, v57
	v_mul_f32_e32 v80, v54, v54
	v_mul_f32_e32 v81, v55, v55
	v_pk_fma_f32 v[68:69], v[58:59], v[58:59], v[72:73] op_sel_hi:[1,1,0]
	v_pk_fma_f32 v[72:73], v[60:61], v[60:61], v[74:75] op_sel_hi:[1,1,0]
	v_pk_add_f32 v[66:67], v[66:67], v[66:67] op_sel:[0,1] op_sel_hi:[1,0]
	v_pk_add_f32 v[64:65], v[64:65], v[64:65] op_sel:[0,1] op_sel_hi:[1,0]
	v_mov_b32_e32 v69, v75
	v_mov_b32_e32 v73, v77
	v_mov_b32_e32 v67, v80
	v_mov_b32_e32 v65, v81
	v_pk_add_f32 v[68:69], v[68:69], v[72:73]
	v_pk_add_f32 v[64:65], v[66:67], v[64:65]
	v_pk_add_f32 v[10:11], v[10:11], 1.0 op_sel_hi:[1,0]
	v_pk_add_f32 v[64:65], v[64:65], v[68:69]
	v_pk_add_f32 v[8:9], v[8:9], 1.0 op_sel_hi:[1,0]
	v_add_f32_e32 v64, v64, v65
	ds_bpermute_b32 v65, v38, v64
	s_waitcnt lgkmcnt(0)
	v_add_f32_e32 v64, v64, v65
	ds_bpermute_b32 v65, v39, v64
	s_waitcnt lgkmcnt(0)
	v_add_f32_e32 v64, v64, v65
	ds_bpermute_b32 v65, v40, v64
	s_waitcnt lgkmcnt(0)
	v_add_f32_e32 v64, v64, v65
	ds_bpermute_b32 v65, v41, v64
	s_waitcnt lgkmcnt(0)
	v_add_f32_e32 v64, v64, v65
	ds_bpermute_b32 v65, v42, v64
	s_waitcnt lgkmcnt(0)
	v_add_f32_e32 v64, v64, v65
	ds_bpermute_b32 v65, v43, v64
	s_waitcnt lgkmcnt(0)
	v_add_f32_e32 v64, v64, v65
	v_fmamk_f32 v64, v64, 0x3a800000, v44
	v_mul_f32_e32 v65, 0x4f800000, v64
	v_cmp_gt_f32_e32 vcc, s17, v64
	s_nop 1
	v_cndmask_b32_e32 v64, v64, v65, vcc
	v_sqrt_f32_e32 v65, v64
	s_nop 0
	v_add_u32_e32 v66, -1, v65
	v_add_u32_e32 v67, 1, v65
	v_fma_f32 v68, -v66, v65, v64
	v_fma_f32 v69, -v67, v65, v64
	v_cmp_ge_f32_e64 s[4:5], 0, v68
	s_nop 1
	v_cndmask_b32_e64 v65, v65, v66, s[4:5]
	v_cmp_lt_f32_e64 s[4:5], 0, v69
	s_nop 1
	v_cndmask_b32_e64 v65, v65, v67, s[4:5]
	v_mul_f32_e32 v66, 0x37800000, v65
	v_cndmask_b32_e32 v65, v65, v66, vcc
	v_cmp_class_f32_e32 vcc, v64, v45
	s_nop 1
	v_cndmask_b32_e32 v64, v65, v64, vcc
	v_div_scale_f32 v65, s[4:5], v64, v64, 1.0
	v_rcp_f32_e32 v67, v65
	v_div_scale_f32 v66, vcc, 1.0, v64, 1.0
	v_fma_f32 v68, -v65, v67, 1.0
	v_fmac_f32_e32 v67, v68, v67
	v_mul_f32_e32 v68, v66, v67
	v_fma_f32 v69, -v65, v68, v66
	v_fmac_f32_e32 v68, v69, v67
	v_fma_f32 v65, -v65, v68, v66
	v_div_fmas_f32 v65, v65, v67, v68
	v_div_fixup_f32 v64, v65, v64, 1.0
	v_pk_mul_f32 v[48:49], v[48:49], v[64:65] op_sel_hi:[1,0]
	v_pk_mul_f32 v[46:47], v[46:47], v[64:65] op_sel_hi:[1,0]
	v_pk_mul_f32 v[2:3], v[2:3], v[48:49]
	v_pk_mul_f32 v[0:1], v[0:1], v[46:47]
	v_pk_fma_f32 v[2:3], v[10:11], v[2:3], v[6:7]
	v_pk_fma_f32 v[0:1], v[8:9], v[0:1], v[4:5]
	v_bfe_u32 v6, v2, 16, 1
	v_bfe_u32 v4, v0, 16, 1
	v_bfe_u32 v5, v1, 16, 1
	v_bfe_u32 v7, v3, 16, 1
	v_add3_u32 v0, v0, v4, s18
	v_add3_u32 v2, v2, v6, s18
	v_add3_u32 v1, v1, v5, s18
	v_add3_u32 v3, v3, v7, s18
	v_lshrrev_b32_e32 v0, 16, v0
	v_lshrrev_b32_e32 v2, 16, v2
	v_and_or_b32 v0, v1, s19, v0
	v_and_or_b32 v1, v3, s19, v2
	global_store_dwordx2 v[36:37], v[0:1], off
	global_load_dwordx4 v[0:3], v[16:17], off offset:1024
	s_nop 0
	global_load_dwordx4 v[4:7], v[22:23], off offset:1024
	global_load_dwordx4 v[8:11], v[24:25], off offset:1024
	v_pk_mul_f32 v[52:53], v[52:53], v[64:65] op_sel_hi:[1,0]
	v_pk_mul_f32 v[50:51], v[50:51], v[64:65] op_sel_hi:[1,0]
	v_pk_mul_f32 v[60:61], v[60:61], v[64:65] op_sel_hi:[1,0]
	v_pk_mul_f32 v[58:59], v[58:59], v[64:65] op_sel_hi:[1,0]
	v_pk_mul_f32 v[56:57], v[56:57], v[64:65] op_sel_hi:[1,0]
	v_pk_mul_f32 v[54:55], v[54:55], v[64:65] op_sel_hi:[1,0]
	s_waitcnt vmcnt(2)
	v_pk_mul_f32 v[0:1], v[0:1], v[50:51]
	v_pk_mul_f32 v[2:3], v[2:3], v[52:53]
	s_waitcnt vmcnt(1)
	v_pk_add_f32 v[6:7], v[6:7], 1.0 op_sel_hi:[1,0]
	v_pk_add_f32 v[4:5], v[4:5], 1.0 op_sel_hi:[1,0]
	s_waitcnt vmcnt(0)
; __device__ __forceinline__ unsigned pk2(float lo, float hi) { return f2bf(lo) | (f2bf(hi) << 16); }
; template <bool MIX>
; __device__ __forceinline__ void norm_phase(const float* xin, int l, int sub, LAS unsigned char* lds, int vcu, int G, int tid, int wave, int lane) {
;     ...
;         for (int i = 0; i < 8; ++i) { const int rl = wave * 8 + i, row = blk * 64 + rl;
;             const f32x4* xr = (const f32x4*)(xin + (size_t)row * 1024) + lane;
;             f32x4 v[4]; float ss = 0.f;
; #pragma unroll
;             for (int j = 0; j < 4; ++j) { v[j] = xr[64 * j]; ss += (v[j].x * v[j].x + v[j].y * v[j].y) + (v[j].z * v[j].z + v[j].w * v[j].w); }
;             const float rstd = 1.0f / sqrtf(wave_sum(ss) * (1.0f / 1024.0f) + 1e-6f);
;             unsigned long long* o8 = (unsigned long long*)(XN + (size_t)row * 1024) + lane;
; #pragma unroll
;             for (int j = 0; j < 4; ++j) { const f32x4 g = ((const f32x4*)gain)[64 * j + lane], sc = ((const f32x4*)(scale + b * 9216))[64 * j + lane], sh = ((const f32x4*)(shift + b * 9216))[64 * j + lane];
;                 v[j] = (v[j] * rstd * g) * (1.0f + sc) + sh;
;                 o8[64 * j] = (unsigned long long)pk2(v[j].x, v[j].y) | ((unsigned long long)pk2(v[j].z, v[j].w) << 32); }
	v_pk_fma_f32 v[2:3], v[6:7], v[2:3], v[10:11]
	v_pk_fma_f32 v[0:1], v[4:5], v[0:1], v[8:9]
	v_bfe_u32 v6, v2, 16, 1
	v_bfe_u32 v4, v0, 16, 1
	v_bfe_u32 v5, v1, 16, 1
	v_bfe_u32 v7, v3, 16, 1
	v_add3_u32 v0, v0, v4, s18
	v_add3_u32 v2, v2, v6, s18
	v_add3_u32 v1, v1, v5, s18
	v_add3_u32 v3, v3, v7, s18
	v_lshrrev_b32_e32 v0, 16, v0
	v_lshrrev_b32_e32 v2, 16, v2
	v_and_or_b32 v0, v1, s19, v0
	v_and_or_b32 v1, v3, s19, v2
	global_store_dwordx2 v[36:37], v[0:1], off offset:512
	global_load_dwordx4 v[0:3], v[16:17], off offset:2048
	s_nop 0
	global_load_dwordx4 v[4:7], v[22:23], off offset:2048
	global_load_dwordx4 v[8:11], v[24:25], off offset:2048
	s_waitcnt vmcnt(2)
	v_pk_mul_f32 v[0:1], v[0:1], v[58:59]
	v_pk_mul_f32 v[2:3], v[2:3], v[60:61]
	s_waitcnt vmcnt(1)
	v_pk_add_f32 v[6:7], v[6:7], 1.0 op_sel_hi:[1,0]
	v_pk_add_f32 v[4:5], v[4:5], 1.0 op_sel_hi:[1,0]
	s_waitcnt vmcnt(0)
	v_pk_fma_f32 v[2:3], v[6:7], v[2:3], v[10:11]
	v_pk_fma_f32 v[0:1], v[4:5], v[0:1], v[8:9]
	v_bfe_u32 v6, v2, 16, 1
	v_bfe_u32 v4, v0, 16, 1
	v_bfe_u32 v5, v1, 16, 1
	v_bfe_u32 v7, v3, 16, 1
	v_add3_u32 v0, v0, v4, s18
	v_add3_u32 v2, v2, v6, s18
	v_add3_u32 v1, v1, v5, s18
	v_add3_u32 v3, v3, v7, s18
	v_lshrrev_b32_e32 v0, 16, v0
	v_lshrrev_b32_e32 v2, 16, v2
	v_and_or_b32 v0, v1, s19, v0
	v_and_or_b32 v1, v3, s19, v2
	global_store_dwordx2 v[36:37], v[0:1], off offset:1024
	global_load_dwordx4 v[0:3], v[16:17], off offset:3072
	s_nop 0
	global_load_dwordx4 v[4:7], v[22:23], off offset:3072
	global_load_dwordx4 v[8:11], v[24:25], off offset:3072
	s_waitcnt vmcnt(2)
	v_pk_mul_f32 v[0:1], v[54:55], v[0:1]
	v_pk_mul_f32 v[2:3], v[56:57], v[2:3]
	s_waitcnt vmcnt(1)
	v_pk_add_f32 v[6:7], v[6:7], 1.0 op_sel_hi:[1,0]
	v_pk_add_f32 v[4:5], v[4:5], 1.0 op_sel_hi:[1,0]
	s_waitcnt vmcnt(0)
	v_pk_fma_f32 v[2:3], v[2:3], v[6:7], v[10:11]
	v_pk_fma_f32 v[0:1], v[0:1], v[4:5], v[8:9]
	v_bfe_u32 v6, v2, 16, 1
	v_bfe_u32 v4, v0, 16, 1
	v_bfe_u32 v5, v1, 16, 1
	v_bfe_u32 v7, v3, 16, 1
	v_add3_u32 v0, v0, v4, s18
	v_add3_u32 v2, v2, v6, s18
	v_add3_u32 v1, v1, v5, s18
	v_add3_u32 v3, v3, v7, s18
	v_lshrrev_b32_e32 v0, 16, v0
	v_lshrrev_b32_e32 v2, 16, v2
	v_and_or_b32 v0, v1, s19, v0
	v_and_or_b32 v1, v3, s19, v2
	global_store_dwordx2 v[36:37], v[0:1], off offset:1536
	global_load_dwordx4 v[0:3], v[62:63], off nt
	s_nop 0
	global_load_dwordx4 v[4:7], v[62:63], off offset:1024 nt
	global_load_dwordx4 v[8:11], v[62:63], off offset:3072 nt
	global_load_dwordx4 v[46:49], v[22:23], off
	global_load_dwordx4 v[50:53], v[62:63], off offset:2048 nt
	global_load_dwordx4 v[54:57], v[16:17], off
	global_load_dwordx4 v[58:61], v[24:25], off
	s_waitcnt vmcnt(6)
	v_pk_mul_f32 v[36:37], v[2:3], v[2:3]
	v_pk_mul_f32 v[62:63], v[0:1], v[0:1]
	s_waitcnt vmcnt(5)
	v_pk_mul_f32 v[64:65], v[6:7], v[6:7]
	v_pk_mul_f32 v[66:67], v[4:5], v[4:5]
	v_pk_mov_b32 v[72:73], v[62:63], v[36:37] op_sel:[1,0]
	v_mov_b32_e32 v63, v37
	v_pk_mov_b32 v[36:37], v[66:67], v[64:65] op_sel:[1,0]
	v_mov_b32_e32 v67, v65
	s_waitcnt vmcnt(4)
	v_mul_f32_e32 v71, v8, v8
	s_waitcnt vmcnt(2)
	v_mul_f32_e32 v68, v51, v51
	v_mul_f32_e32 v70, v53, v53
	v_pk_add_f32 v[62:63], v[72:73], v[62:63]
	v_pk_add_f32 v[36:37], v[36:37], v[66:67]
	v_mul_f32_e32 v74, v9, v9
	v_mul_f32_e32 v75, v10, v10
	v_mul_f32_e32 v77, v11, v11
	v_pk_fma_f32 v[64:65], v[50:51], v[50:51], v[68:69] op_sel_hi:[1,1,0]
	v_pk_fma_f32 v[68:69], v[52:53], v[52:53], v[70:71] op_sel_hi:[1,1,0]
	v_pk_add_f32 v[62:63], v[62:63], v[62:63] op_sel:[0,1] op_sel_hi:[1,0]
	v_pk_add_f32 v[36:37], v[36:37], v[36:37] op_sel:[0,1] op_sel_hi:[1,0]
	v_mov_b32_e32 v65, v75
	v_mov_b32_e32 v69, v77
	v_mov_b32_e32 v63, v71
	v_mov_b32_e32 v37, v74
	v_pk_add_f32 v[64:65], v[64:65], v[68:69]
	v_pk_add_f32 v[36:37], v[62:63], v[36:37]
	v_pk_add_f32 v[48:49], v[48:49], 1.0 op_sel_hi:[1,0]
	v_pk_add_f32 v[36:37], v[36:37], v[64:65]
	v_pk_add_f32 v[46:47], v[46:47], 1.0 op_sel_hi:[1,0]
	v_add_f32_e32 v36, v36, v37
	ds_bpermute_b32 v37, v38, v36
	s_waitcnt lgkmcnt(0)
	v_add_f32_e32 v36, v36, v37
	ds_bpermute_b32 v37, v39, v36
	s_waitcnt lgkmcnt(0)
	v_add_f32_e32 v36, v36, v37
	ds_bpermute_b32 v37, v40, v36
	s_waitcnt lgkmcnt(0)
	v_add_f32_e32 v36, v36, v37
	ds_bpermute_b32 v37, v41, v36
	s_waitcnt lgkmcnt(0)
	v_add_f32_e32 v36, v36, v37
	ds_bpermute_b32 v37, v42, v36
	s_waitcnt lgkmcnt(0)
	v_add_f32_e32 v36, v36, v37
	ds_bpermute_b32 v37, v43, v36
	s_waitcnt lgkmcnt(0)
	v_add_f32_e32 v36, v36, v37
	v_fmamk_f32 v36, v36, 0x3a800000, v44
	v_mul_f32_e32 v37, 0x4f800000, v36
	v_cmp_gt_f32_e32 vcc, s17, v36
	s_nop 1
	v_cndmask_b32_e32 v36, v36, v37, vcc
	v_sqrt_f32_e32 v37, v36
	s_nop 0
	v_add_u32_e32 v62, -1, v37
	v_add_u32_e32 v63, 1, v37
	v_fma_f32 v64, -v62, v37, v36
	v_fma_f32 v65, -v63, v37, v36
	v_cmp_ge_f32_e64 s[4:5], 0, v64
	s_nop 1
	v_cndmask_b32_e64 v37, v37, v62, s[4:5]
	v_cmp_lt_f32_e64 s[4:5], 0, v65
	s_nop 1
	v_cndmask_b32_e64 v37, v37, v63, s[4:5]
	v_mul_f32_e32 v62, 0x37800000, v37
	v_cndmask_b32_e32 v37, v37, v62, vcc
	v_cmp_class_f32_e32 vcc, v36, v45
	s_nop 1
	v_cndmask_b32_e32 v36, v37, v36, vcc
	v_div_scale_f32 v37, s[4:5], v36, v36, 1.0
	v_rcp_f32_e32 v63, v37
	v_div_scale_f32 v62, vcc, 1.0, v36, 1.0
	v_fma_f32 v64, -v37, v63, 1.0
	v_fmac_f32_e32 v63, v64, v63
	v_mul_f32_e32 v64, v62, v63
	v_fma_f32 v65, -v37, v64, v62
	v_fmac_f32_e32 v64, v65, v63
	v_fma_f32 v37, -v37, v64, v62
	v_div_fmas_f32 v37, v37, v63, v64
	v_div_fixup_f32 v36, v37, v36, 1.0
	v_pk_mul_f32 v[2:3], v[2:3], v[36:37] op_sel_hi:[1,0]
	v_pk_mul_f32 v[0:1], v[0:1], v[36:37] op_sel_hi:[1,0]
	s_waitcnt vmcnt(1)
	v_pk_mul_f32 v[2:3], v[56:57], v[2:3]
	v_pk_mul_f32 v[0:1], v[54:55], v[0:1]
	s_waitcnt vmcnt(0)
; __device__ __forceinline__ unsigned pk2(float lo, float hi) { return f2bf(lo) | (f2bf(hi) << 16); }
; template <bool MIX>
; __device__ __forceinline__ void norm_phase(const float* xin, int l, int sub, LAS unsigned char* lds, int vcu, int G, int tid, int wave, int lane) {
;     ...
;         for (int i = 0; i < 8; ++i) { const int rl = wave * 8 + i, row = blk * 64 + rl;
;             const f32x4* xr = (const f32x4*)(xin + (size_t)row * 1024) + lane;
;             f32x4 v[4]; float ss = 0.f;
; #pragma unroll
;             for (int j = 0; j < 4; ++j) { v[j] = xr[64 * j]; ss += (v[j].x * v[j].x + v[j].y * v[j].y) + (v[j].z * v[j].z + v[j].w * v[j].w); }
;             const float rstd = 1.0f / sqrtf(wave_sum(ss) * (1.0f / 1024.0f) + 1e-6f);
;             unsigned long long* o8 = (unsigned long long*)(XN + (size_t)row * 1024) + lane;
; #pragma unroll
;             for (int j = 0; j < 4; ++j) { const f32x4 g = ((const f32x4*)gain)[64 * j + lane], sc = ((const f32x4*)(scale + b * 9216))[64 * j + lane], sh = ((const f32x4*)(shift + b * 9216))[64 * j + lane];
;                 v[j] = (v[j] * rstd * g) * (1.0f + sc) + sh;
;                 o8[64 * j] = (unsigned long long)pk2(v[j].x, v[j].y) | ((unsigned long long)pk2(v[j].z, v[j].w) << 32); }
	v_pk_fma_f32 v[2:3], v[48:49], v[2:3], v[60:61]
	v_pk_fma_f32 v[0:1], v[46:47], v[0:1], v[58:59]
	v_pk_mul_f32 v[62:63], v[6:7], v[36:37] op_sel_hi:[1,0]
	v_pk_mul_f32 v[64:65], v[4:5], v[36:37] op_sel_hi:[1,0]
	v_bfe_u32 v4, v0, 16, 1
	v_bfe_u32 v6, v2, 16, 1
	v_bfe_u32 v5, v1, 16, 1
	v_bfe_u32 v7, v3, 16, 1
	v_add3_u32 v0, v0, v4, s18
	v_add3_u32 v2, v2, v6, s18
	v_add3_u32 v1, v1, v5, s18
	v_add3_u32 v3, v3, v7, s18
	v_lshrrev_b32_e32 v0, 16, v0
	v_lshrrev_b32_e32 v2, 16, v2
	v_and_or_b32 v0, v1, s19, v0
	v_and_or_b32 v1, v3, s19, v2
	global_store_dwordx2 v[34:35], v[0:1], off
	v_pk_mul_f32 v[52:53], v[52:53], v[36:37] op_sel_hi:[1,0]
	v_pk_mul_f32 v[50:51], v[50:51], v[36:37] op_sel_hi:[1,0]
	v_pk_mul_f32 v[66:67], v[10:11], v[36:37] op_sel_hi:[1,0]
	v_pk_mul_f32 v[36:37], v[8:9], v[36:37] op_sel_hi:[1,0]
	global_load_dwordx4 v[0:3], v[16:17], off offset:1024
	global_load_dwordx4 v[4:7], v[22:23], off offset:1024
	global_load_dwordx4 v[8:11], v[24:25], off offset:1024
	s_waitcnt vmcnt(2)
	v_pk_mul_f32 v[0:1], v[0:1], v[64:65]
	v_pk_mul_f32 v[2:3], v[2:3], v[62:63]
	s_waitcnt vmcnt(1)
	v_pk_add_f32 v[6:7], v[6:7], 1.0 op_sel_hi:[1,0]
	v_pk_add_f32 v[4:5], v[4:5], 1.0 op_sel_hi:[1,0]
	s_waitcnt vmcnt(0)
	v_pk_fma_f32 v[2:3], v[6:7], v[2:3], v[10:11]
	v_pk_fma_f32 v[0:1], v[4:5], v[0:1], v[8:9]
	v_bfe_u32 v6, v2, 16, 1
	v_bfe_u32 v4, v0, 16, 1
	v_bfe_u32 v5, v1, 16, 1
	v_bfe_u32 v7, v3, 16, 1
	v_add3_u32 v0, v0, v4, s18
	v_add3_u32 v2, v2, v6, s18
	v_add3_u32 v1, v1, v5, s18
	v_add3_u32 v3, v3, v7, s18
	v_lshrrev_b32_e32 v0, 16, v0
	v_lshrrev_b32_e32 v2, 16, v2
	v_and_or_b32 v0, v1, s19, v0
	v_and_or_b32 v1, v3, s19, v2
	global_store_dwordx2 v[34:35], v[0:1], off offset:512
	global_load_dwordx4 v[0:3], v[16:17], off offset:2048
	s_nop 0
	global_load_dwordx4 v[4:7], v[22:23], off offset:2048
	global_load_dwordx4 v[8:11], v[24:25], off offset:2048
	s_waitcnt vmcnt(2)
	v_pk_mul_f32 v[0:1], v[0:1], v[50:51]
	v_pk_mul_f32 v[2:3], v[2:3], v[52:53]
	s_waitcnt vmcnt(1)
	v_pk_add_f32 v[6:7], v[6:7], 1.0 op_sel_hi:[1,0]
	v_pk_add_f32 v[4:5], v[4:5], 1.0 op_sel_hi:[1,0]
	s_waitcnt vmcnt(0)
	v_pk_fma_f32 v[2:3], v[6:7], v[2:3], v[10:11]
	v_pk_fma_f32 v[0:1], v[4:5], v[0:1], v[8:9]
	v_bfe_u32 v6, v2, 16, 1
	v_bfe_u32 v4, v0, 16, 1
	v_bfe_u32 v5, v1, 16, 1
	v_bfe_u32 v7, v3, 16, 1
	v_add3_u32 v0, v0, v4, s18
	v_add3_u32 v2, v2, v6, s18
	v_add3_u32 v1, v1, v5, s18
	v_add3_u32 v3, v3, v7, s18
	v_lshrrev_b32_e32 v0, 16, v0
	v_lshrrev_b32_e32 v2, 16, v2
	v_and_or_b32 v0, v1, s19, v0
	v_and_or_b32 v1, v3, s19, v2
	global_store_dwordx2 v[34:35], v[0:1], off offset:1024
	global_load_dwordx4 v[0:3], v[16:17], off offset:3072
	s_nop 0
	global_load_dwordx4 v[4:7], v[22:23], off offset:3072
	global_load_dwordx4 v[8:11], v[24:25], off offset:3072
	s_waitcnt vmcnt(2)
	v_pk_mul_f32 v[0:1], v[36:37], v[0:1]
	v_pk_mul_f32 v[2:3], v[66:67], v[2:3]
	s_waitcnt vmcnt(1)
	v_pk_add_f32 v[6:7], v[6:7], 1.0 op_sel_hi:[1,0]
	v_pk_add_f32 v[4:5], v[4:5], 1.0 op_sel_hi:[1,0]
	s_waitcnt vmcnt(0)
	v_pk_fma_f32 v[2:3], v[2:3], v[6:7], v[10:11]
	v_pk_fma_f32 v[0:1], v[0:1], v[4:5], v[8:9]
	v_bfe_u32 v6, v2, 16, 1
	v_bfe_u32 v4, v0, 16, 1
	v_bfe_u32 v5, v1, 16, 1
	v_bfe_u32 v7, v3, 16, 1
	v_add3_u32 v0, v0, v4, s18
	v_add3_u32 v2, v2, v6, s18
	v_add3_u32 v1, v1, v5, s18
	v_add3_u32 v3, v3, v7, s18
	v_lshrrev_b32_e32 v0, 16, v0
	v_lshrrev_b32_e32 v2, 16, v2
	v_and_or_b32 v0, v1, s19, v0
	v_and_or_b32 v1, v3, s19, v2
	global_store_dwordx2 v[34:35], v[0:1], off offset:1536
	global_load_dwordx4 v[0:3], v[32:33], off nt
	s_nop 0
	global_load_dwordx4 v[4:7], v[32:33], off offset:1024 nt
	global_load_dwordx4 v[8:11], v[32:33], off offset:3072 nt
	global_load_dwordx4 v[34:37], v[32:33], off offset:2048 nt
	global_load_dwordx4 v[46:49], v[22:23], off
	global_load_dwordx4 v[50:53], v[16:17], off
	global_load_dwordx4 v[54:57], v[24:25], off
	s_waitcnt vmcnt(6)
	v_pk_mul_f32 v[32:33], v[2:3], v[2:3]
	v_pk_mul_f32 v[58:59], v[0:1], v[0:1]
	s_waitcnt vmcnt(5)
	v_pk_mul_f32 v[60:61], v[6:7], v[6:7]
	v_pk_mul_f32 v[62:63], v[4:5], v[4:5]
	v_pk_mov_b32 v[68:69], v[58:59], v[32:33] op_sel:[1,0]
	v_mov_b32_e32 v59, v33
	v_pk_mov_b32 v[32:33], v[62:63], v[60:61] op_sel:[1,0]
	v_mov_b32_e32 v63, v61
	s_waitcnt vmcnt(4)
	v_mul_f32_e32 v67, v8, v8
	s_waitcnt vmcnt(3)
	v_mul_f32_e32 v64, v35, v35
	v_mul_f32_e32 v66, v37, v37
	v_pk_add_f32 v[58:59], v[68:69], v[58:59]
	v_pk_add_f32 v[32:33], v[32:33], v[62:63]
	v_mul_f32_e32 v70, v9, v9
	v_mul_f32_e32 v71, v10, v10
	v_mul_f32_e32 v72, v11, v11
	v_pk_fma_f32 v[60:61], v[34:35], v[34:35], v[64:65] op_sel_hi:[1,1,0]
	v_pk_fma_f32 v[64:65], v[36:37], v[36:37], v[66:67] op_sel_hi:[1,1,0]
	v_pk_add_f32 v[58:59], v[58:59], v[58:59] op_sel:[0,1] op_sel_hi:[1,0]
	v_pk_add_f32 v[32:33], v[32:33], v[32:33] op_sel:[0,1] op_sel_hi:[1,0]
	v_mov_b32_e32 v61, v71
	v_mov_b32_e32 v65, v72
	v_mov_b32_e32 v59, v67
	v_mov_b32_e32 v33, v70
	v_pk_add_f32 v[60:61], v[60:61], v[64:65]
	v_pk_add_f32 v[32:33], v[58:59], v[32:33]
	s_waitcnt vmcnt(2)
	v_pk_add_f32 v[48:49], v[48:49], 1.0 op_sel_hi:[1,0]
	v_pk_add_f32 v[32:33], v[32:33], v[60:61]
	v_pk_add_f32 v[46:47], v[46:47], 1.0 op_sel_hi:[1,0]
	v_add_f32_e32 v32, v32, v33
	ds_bpermute_b32 v33, v38, v32
	s_waitcnt lgkmcnt(0)
	v_add_f32_e32 v32, v32, v33
	ds_bpermute_b32 v33, v39, v32
	s_waitcnt lgkmcnt(0)
	v_add_f32_e32 v32, v32, v33
	ds_bpermute_b32 v33, v40, v32
	s_waitcnt lgkmcnt(0)
	v_add_f32_e32 v32, v32, v33
	ds_bpermute_b32 v33, v41, v32
	s_waitcnt lgkmcnt(0)
	v_add_f32_e32 v32, v32, v33
	ds_bpermute_b32 v33, v42, v32
	s_waitcnt lgkmcnt(0)
	v_add_f32_e32 v32, v32, v33
	ds_bpermute_b32 v33, v43, v32
	s_waitcnt lgkmcnt(0)
; __device__ __forceinline__ unsigned pk2(float lo, float hi) { return f2bf(lo) | (f2bf(hi) << 16); }
; template <bool MIX>
; __device__ __forceinline__ void norm_phase(const float* xin, int l, int sub, LAS unsigned char* lds, int vcu, int G, int tid, int wave, int lane) {
;     ...
;         for (int i = 0; i < 8; ++i) { const int rl = wave * 8 + i, row = blk * 64 + rl;
;             const f32x4* xr = (const f32x4*)(xin + (size_t)row * 1024) + lane;
;             f32x4 v[4]; float ss = 0.f;
; #pragma unroll
;             for (int j = 0; j < 4; ++j) { v[j] = xr[64 * j]; ss += (v[j].x * v[j].x + v[j].y * v[j].y) + (v[j].z * v[j].z + v[j].w * v[j].w); }
;             const float rstd = 1.0f / sqrtf(wave_sum(ss) * (1.0f / 1024.0f) + 1e-6f);
;             unsigned long long* o8 = (unsigned long long*)(XN + (size_t)row * 1024) + lane;
; #pragma unroll
;             for (int j = 0; j < 4; ++j) { const f32x4 g = ((const f32x4*)gain)[64 * j + lane], sc = ((const f32x4*)(scale + b * 9216))[64 * j + lane], sh = ((const f32x4*)(shift + b * 9216))[64 * j + lane];
;                 v[j] = (v[j] * rstd * g) * (1.0f + sc) + sh;
;                 o8[64 * j] = (unsigned long long)pk2(v[j].x, v[j].y) | ((unsigned long long)pk2(v[j].z, v[j].w) << 32); }
	v_add_f32_e32 v32, v32, v33
	v_fmamk_f32 v32, v32, 0x3a800000, v44
	v_mul_f32_e32 v33, 0x4f800000, v32
	v_cmp_gt_f32_e32 vcc, s17, v32
	s_nop 1
	v_cndmask_b32_e32 v32, v32, v33, vcc
	v_sqrt_f32_e32 v33, v32
	s_nop 0
	v_add_u32_e32 v58, -1, v33
	v_add_u32_e32 v59, 1, v33
	v_fma_f32 v60, -v58, v33, v32
	v_fma_f32 v61, -v59, v33, v32
	v_cmp_ge_f32_e64 s[4:5], 0, v60
	s_nop 1
	v_cndmask_b32_e64 v33, v33, v58, s[4:5]
	v_cmp_lt_f32_e64 s[4:5], 0, v61
	s_nop 1
	v_cndmask_b32_e64 v33, v33, v59, s[4:5]
	v_mul_f32_e32 v58, 0x37800000, v33
	v_cndmask_b32_e32 v33, v33, v58, vcc
	v_cmp_class_f32_e32 vcc, v32, v45
	s_nop 1
	v_cndmask_b32_e32 v32, v33, v32, vcc
	v_div_scale_f32 v33, s[4:5], v32, v32, 1.0
	v_rcp_f32_e32 v59, v33
	v_div_scale_f32 v58, vcc, 1.0, v32, 1.0
	v_fma_f32 v60, -v33, v59, 1.0
	v_fmac_f32_e32 v59, v60, v59
	v_mul_f32_e32 v60, v58, v59
	v_fma_f32 v61, -v33, v60, v58
	v_fmac_f32_e32 v60, v61, v59
	v_fma_f32 v33, -v33, v60, v58
	v_div_fmas_f32 v33, v33, v59, v60
	v_div_fixup_f32 v32, v33, v32, 1.0
	v_pk_mul_f32 v[2:3], v[2:3], v[32:33] op_sel_hi:[1,0]
	v_pk_mul_f32 v[0:1], v[0:1], v[32:33] op_sel_hi:[1,0]
	s_waitcnt vmcnt(1)
	v_pk_mul_f32 v[2:3], v[52:53], v[2:3]
	v_pk_mul_f32 v[0:1], v[50:51], v[0:1]
	s_waitcnt vmcnt(0)
	v_pk_fma_f32 v[2:3], v[48:49], v[2:3], v[56:57]
	v_pk_fma_f32 v[0:1], v[46:47], v[0:1], v[54:55]
	v_pk_mul_f32 v[58:59], v[6:7], v[32:33] op_sel_hi:[1,0]
	v_pk_mul_f32 v[60:61], v[4:5], v[32:33] op_sel_hi:[1,0]
	v_bfe_u32 v4, v0, 16, 1
	v_bfe_u32 v6, v2, 16, 1
	v_bfe_u32 v5, v1, 16, 1
	v_bfe_u32 v7, v3, 16, 1
	v_add3_u32 v0, v0, v4, s18
	v_add3_u32 v2, v2, v6, s18
	v_add3_u32 v1, v1, v5, s18
	v_add3_u32 v3, v3, v7, s18
	v_lshrrev_b32_e32 v0, 16, v0
	v_lshrrev_b32_e32 v2, 16, v2
	v_and_or_b32 v0, v1, s19, v0
	v_and_or_b32 v1, v3, s19, v2
	global_store_dwordx2 v[30:31], v[0:1], off
	v_pk_mul_f32 v[36:37], v[36:37], v[32:33] op_sel_hi:[1,0]
	v_pk_mul_f32 v[34:35], v[34:35], v[32:33] op_sel_hi:[1,0]
	v_pk_mul_f32 v[62:63], v[10:11], v[32:33] op_sel_hi:[1,0]
	v_pk_mul_f32 v[32:33], v[8:9], v[32:33] op_sel_hi:[1,0]
	global_load_dwordx4 v[0:3], v[16:17], off offset:1024
	global_load_dwordx4 v[4:7], v[22:23], off offset:1024
	global_load_dwordx4 v[8:11], v[24:25], off offset:1024
	s_waitcnt vmcnt(2)
	v_pk_mul_f32 v[0:1], v[0:1], v[60:61]
	v_pk_mul_f32 v[2:3], v[2:3], v[58:59]
	s_waitcnt vmcnt(1)
	v_pk_add_f32 v[6:7], v[6:7], 1.0 op_sel_hi:[1,0]
	v_pk_add_f32 v[4:5], v[4:5], 1.0 op_sel_hi:[1,0]
	s_waitcnt vmcnt(0)
	v_pk_fma_f32 v[2:3], v[6:7], v[2:3], v[10:11]
	v_pk_fma_f32 v[0:1], v[4:5], v[0:1], v[8:9]
	v_bfe_u32 v6, v2, 16, 1
	v_bfe_u32 v4, v0, 16, 1
	v_bfe_u32 v5, v1, 16, 1
	v_bfe_u32 v7, v3, 16, 1
	v_add3_u32 v0, v0, v4, s18
	v_add3_u32 v2, v2, v6, s18
	v_add3_u32 v1, v1, v5, s18
	v_add3_u32 v3, v3, v7, s18
	v_lshrrev_b32_e32 v0, 16, v0
	v_lshrrev_b32_e32 v2, 16, v2
	v_and_or_b32 v0, v1, s19, v0
	v_and_or_b32 v1, v3, s19, v2
	global_store_dwordx2 v[30:31], v[0:1], off offset:512
	global_load_dwordx4 v[0:3], v[16:17], off offset:2048
	s_nop 0
	global_load_dwordx4 v[4:7], v[22:23], off offset:2048
	global_load_dwordx4 v[8:11], v[24:25], off offset:2048
	s_waitcnt vmcnt(2)
	v_pk_mul_f32 v[0:1], v[0:1], v[34:35]
	v_pk_mul_f32 v[2:3], v[2:3], v[36:37]
	s_waitcnt vmcnt(1)
	v_pk_add_f32 v[6:7], v[6:7], 1.0 op_sel_hi:[1,0]
	v_pk_add_f32 v[4:5], v[4:5], 1.0 op_sel_hi:[1,0]
	s_waitcnt vmcnt(0)
	v_pk_fma_f32 v[2:3], v[6:7], v[2:3], v[10:11]
	v_pk_fma_f32 v[0:1], v[4:5], v[0:1], v[8:9]
	v_bfe_u32 v6, v2, 16, 1
	v_bfe_u32 v4, v0, 16, 1
	v_bfe_u32 v5, v1, 16, 1
	v_bfe_u32 v7, v3, 16, 1
	v_add3_u32 v0, v0, v4, s18
	v_add3_u32 v2, v2, v6, s18
	v_add3_u32 v1, v1, v5, s18
	v_add3_u32 v3, v3, v7, s18
	v_lshrrev_b32_e32 v0, 16, v0
	v_lshrrev_b32_e32 v2, 16, v2
	v_and_or_b32 v0, v1, s19, v0
	v_and_or_b32 v1, v3, s19, v2
	global_store_dwordx2 v[30:31], v[0:1], off offset:1024
	global_load_dwordx4 v[0:3], v[16:17], off offset:3072
	s_nop 0
	global_load_dwordx4 v[4:7], v[22:23], off offset:3072
	global_load_dwordx4 v[8:11], v[24:25], off offset:3072
	s_waitcnt vmcnt(2)
	v_pk_mul_f32 v[0:1], v[32:33], v[0:1]
	v_pk_mul_f32 v[2:3], v[62:63], v[2:3]
	s_waitcnt vmcnt(1)
	v_pk_add_f32 v[6:7], v[6:7], 1.0 op_sel_hi:[1,0]
	v_pk_add_f32 v[4:5], v[4:5], 1.0 op_sel_hi:[1,0]
	s_waitcnt vmcnt(0)
	v_pk_fma_f32 v[2:3], v[2:3], v[6:7], v[10:11]
	v_pk_fma_f32 v[0:1], v[0:1], v[4:5], v[8:9]
	v_bfe_u32 v6, v2, 16, 1
	v_bfe_u32 v4, v0, 16, 1
	v_bfe_u32 v5, v1, 16, 1
	v_bfe_u32 v7, v3, 16, 1
	v_add3_u32 v0, v0, v4, s18
	v_add3_u32 v2, v2, v6, s18
	v_add3_u32 v1, v1, v5, s18
	v_add3_u32 v3, v3, v7, s18
	v_lshrrev_b32_e32 v0, 16, v0
	v_lshrrev_b32_e32 v2, 16, v2
	v_and_or_b32 v0, v1, s19, v0
	v_and_or_b32 v1, v3, s19, v2
	global_store_dwordx2 v[30:31], v[0:1], off offset:1536
	global_load_dwordx4 v[0:3], v[28:29], off nt
	s_nop 0
	global_load_dwordx4 v[4:7], v[28:29], off offset:1024 nt
	global_load_dwordx4 v[8:11], v[28:29], off offset:3072 nt
	global_load_dwordx4 v[30:33], v[28:29], off offset:2048 nt
	global_load_dwordx4 v[34:37], v[22:23], off
	global_load_dwordx4 v[46:49], v[16:17], off
	global_load_dwordx4 v[50:53], v[24:25], off
	s_waitcnt vmcnt(6)
	v_pk_mul_f32 v[28:29], v[2:3], v[2:3]
	v_pk_mul_f32 v[54:55], v[0:1], v[0:1]
	s_waitcnt vmcnt(5)
	v_pk_mul_f32 v[56:57], v[6:7], v[6:7]
	v_pk_mul_f32 v[58:59], v[4:5], v[4:5]
	v_pk_mov_b32 v[64:65], v[54:55], v[28:29] op_sel:[1,0]
	v_mov_b32_e32 v55, v29
	v_pk_mov_b32 v[28:29], v[58:59], v[56:57] op_sel:[1,0]
	v_mov_b32_e32 v59, v57
	s_waitcnt vmcnt(4)
	v_mul_f32_e32 v63, v8, v8
	s_waitcnt vmcnt(3)
; __device__ __forceinline__ unsigned pk2(float lo, float hi) { return f2bf(lo) | (f2bf(hi) << 16); }
; template <bool MIX>
; __device__ __forceinline__ void norm_phase(const float* xin, int l, int sub, LAS unsigned char* lds, int vcu, int G, int tid, int wave, int lane) {
;     ...
;     for (int blk = vcu; blk < 256; blk += G) {
;         const int b = blk >> 7;
; #pragma unroll (MIX ? 2 : 4)
;         for (int i = 0; i < 8; ++i) { const int rl = wave * 8 + i, row = blk * 64 + rl;
;             const f32x4* xr = (const f32x4*)(xin + (size_t)row * 1024) + lane;
;             f32x4 v[4]; float ss = 0.f;
; #pragma unroll
;             for (int j = 0; j < 4; ++j) { v[j] = xr[64 * j]; ss += (v[j].x * v[j].x + v[j].y * v[j].y) + (v[j].z * v[j].z + v[j].w * v[j].w); }
;             const float rstd = 1.0f / sqrtf(wave_sum(ss) * (1.0f / 1024.0f) + 1e-6f);
;             unsigned long long* o8 = (unsigned long long*)(XN + (size_t)row * 1024) + lane;
; #pragma unroll
;             for (int j = 0; j < 4; ++j) { const f32x4 g = ((const f32x4*)gain)[64 * j + lane], sc = ((const f32x4*)(scale + b * 9216))[64 * j + lane], sh = ((const f32x4*)(shift + b * 9216))[64 * j + lane];
;                 v[j] = (v[j] * rstd * g) * (1.0f + sc) + sh;
;                 o8[64 * j] = (unsigned long long)pk2(v[j].x, v[j].y) | ((unsigned long long)pk2(v[j].z, v[j].w) << 32); }
	v_mul_f32_e32 v60, v31, v31
	v_mul_f32_e32 v62, v33, v33
	v_pk_add_f32 v[54:55], v[64:65], v[54:55]
	v_pk_add_f32 v[28:29], v[28:29], v[58:59]
	v_mul_f32_e32 v66, v9, v9
	v_mul_f32_e32 v67, v10, v10
	v_mul_f32_e32 v68, v11, v11
	v_pk_fma_f32 v[56:57], v[30:31], v[30:31], v[60:61] op_sel_hi:[1,1,0]
	v_pk_fma_f32 v[60:61], v[32:33], v[32:33], v[62:63] op_sel_hi:[1,1,0]
	v_pk_add_f32 v[54:55], v[54:55], v[54:55] op_sel:[0,1] op_sel_hi:[1,0]
	v_pk_add_f32 v[28:29], v[28:29], v[28:29] op_sel:[0,1] op_sel_hi:[1,0]
	v_mov_b32_e32 v57, v67
	v_mov_b32_e32 v61, v68
	v_mov_b32_e32 v55, v63
	v_mov_b32_e32 v29, v66
	v_pk_add_f32 v[56:57], v[56:57], v[60:61]
	v_pk_add_f32 v[28:29], v[54:55], v[28:29]
	s_waitcnt vmcnt(2)
	v_pk_add_f32 v[36:37], v[36:37], 1.0 op_sel_hi:[1,0]
	v_pk_add_f32 v[28:29], v[28:29], v[56:57]
	v_pk_add_f32 v[34:35], v[34:35], 1.0 op_sel_hi:[1,0]
	v_add_f32_e32 v28, v28, v29
	ds_bpermute_b32 v29, v38, v28
	s_waitcnt lgkmcnt(0)
	v_add_f32_e32 v28, v28, v29
	ds_bpermute_b32 v29, v39, v28
	s_waitcnt lgkmcnt(0)
	v_add_f32_e32 v28, v28, v29
	ds_bpermute_b32 v29, v40, v28
	s_waitcnt lgkmcnt(0)
	v_add_f32_e32 v28, v28, v29
	ds_bpermute_b32 v29, v41, v28
	s_waitcnt lgkmcnt(0)
	v_add_f32_e32 v28, v28, v29
	ds_bpermute_b32 v29, v42, v28
	s_waitcnt lgkmcnt(0)
	v_add_f32_e32 v28, v28, v29
	ds_bpermute_b32 v29, v43, v28
	s_waitcnt lgkmcnt(0)
	v_add_f32_e32 v28, v28, v29
	v_fmamk_f32 v28, v28, 0x3a800000, v44
	v_mul_f32_e32 v29, 0x4f800000, v28
	v_cmp_gt_f32_e32 vcc, s17, v28
	s_nop 1
	v_cndmask_b32_e32 v28, v28, v29, vcc
	v_sqrt_f32_e32 v29, v28
	s_nop 0
	v_add_u32_e32 v54, -1, v29
	v_add_u32_e32 v55, 1, v29
	v_fma_f32 v56, -v54, v29, v28
	v_fma_f32 v57, -v55, v29, v28
	v_cmp_ge_f32_e64 s[4:5], 0, v56
	s_nop 1
	v_cndmask_b32_e64 v29, v29, v54, s[4:5]
	v_cmp_lt_f32_e64 s[4:5], 0, v57
	s_nop 1
	v_cndmask_b32_e64 v29, v29, v55, s[4:5]
	v_mul_f32_e32 v54, 0x37800000, v29
	v_cndmask_b32_e32 v29, v29, v54, vcc
	v_cmp_class_f32_e32 vcc, v28, v45
	s_nop 1
	v_cndmask_b32_e32 v28, v29, v28, vcc
	v_div_scale_f32 v29, s[4:5], v28, v28, 1.0
	v_rcp_f32_e32 v55, v29
	v_div_scale_f32 v54, vcc, 1.0, v28, 1.0
	v_fma_f32 v56, -v29, v55, 1.0
	v_fmac_f32_e32 v55, v56, v55
	v_mul_f32_e32 v56, v54, v55
	v_fma_f32 v57, -v29, v56, v54
	v_fmac_f32_e32 v56, v57, v55
	v_fma_f32 v29, -v29, v56, v54
	v_div_fmas_f32 v29, v29, v55, v56
	v_div_fixup_f32 v54, v29, v28, 1.0
	v_pk_mul_f32 v[2:3], v[2:3], v[54:55] op_sel_hi:[1,0]
	v_pk_mul_f32 v[0:1], v[0:1], v[54:55] op_sel_hi:[1,0]
	s_waitcnt vmcnt(1)
	v_pk_mul_f32 v[2:3], v[48:49], v[2:3]
	v_pk_mul_f32 v[0:1], v[46:47], v[0:1]
	s_waitcnt vmcnt(0)
	v_pk_fma_f32 v[2:3], v[36:37], v[2:3], v[52:53]
	v_pk_fma_f32 v[0:1], v[34:35], v[0:1], v[50:51]
	v_bfe_u32 v34, v2, 16, 1
	v_bfe_u32 v28, v0, 16, 1
	v_bfe_u32 v29, v1, 16, 1
	v_bfe_u32 v35, v3, 16, 1
	v_add3_u32 v0, v0, v28, s18
	v_add3_u32 v2, v2, v34, s18
	v_add3_u32 v1, v1, v29, s18
	v_add3_u32 v3, v3, v35, s18
	v_lshrrev_b32_e32 v0, 16, v0
	v_lshrrev_b32_e32 v2, 16, v2
	v_and_or_b32 v0, v1, s19, v0
	v_and_or_b32 v1, v3, s19, v2
	global_store_dwordx2 v[26:27], v[0:1], off
	global_load_dwordx4 v[0:3], v[16:17], off offset:1024
	s_nop 0
	global_load_dwordx4 v[34:37], v[22:23], off offset:1024
	global_load_dwordx4 v[46:49], v[24:25], off offset:1024
	v_pk_mul_f32 v[6:7], v[6:7], v[54:55] op_sel_hi:[1,0]
	v_pk_mul_f32 v[4:5], v[4:5], v[54:55] op_sel_hi:[1,0]
	v_pk_mul_f32 v[28:29], v[32:33], v[54:55] op_sel_hi:[1,0]
	v_pk_mul_f32 v[30:31], v[30:31], v[54:55] op_sel_hi:[1,0]
	v_pk_mul_f32 v[10:11], v[10:11], v[54:55] op_sel_hi:[1,0]
	v_pk_mul_f32 v[8:9], v[8:9], v[54:55] op_sel_hi:[1,0]
	s_waitcnt vmcnt(2)
	v_pk_mul_f32 v[0:1], v[0:1], v[4:5]
	v_pk_mul_f32 v[2:3], v[2:3], v[6:7]
	s_waitcnt vmcnt(1)
	v_pk_add_f32 v[4:5], v[36:37], 1.0 op_sel_hi:[1,0]
	v_pk_add_f32 v[6:7], v[34:35], 1.0 op_sel_hi:[1,0]
	s_waitcnt vmcnt(0)
	v_pk_fma_f32 v[2:3], v[4:5], v[2:3], v[48:49]
	v_pk_fma_f32 v[0:1], v[6:7], v[0:1], v[46:47]
	v_bfe_u32 v6, v2, 16, 1
	v_bfe_u32 v4, v0, 16, 1
	v_bfe_u32 v5, v1, 16, 1
	v_bfe_u32 v7, v3, 16, 1
	v_add3_u32 v0, v0, v4, s18
	v_add3_u32 v2, v2, v6, s18
	v_add3_u32 v1, v1, v5, s18
	v_add3_u32 v3, v3, v7, s18
	v_lshrrev_b32_e32 v0, 16, v0
	v_lshrrev_b32_e32 v2, 16, v2
	v_and_or_b32 v0, v1, s19, v0
	v_and_or_b32 v1, v3, s19, v2
	global_store_dwordx2 v[26:27], v[0:1], off offset:512
	global_load_dwordx4 v[0:3], v[16:17], off offset:2048
	s_nop 0
	global_load_dwordx4 v[4:7], v[22:23], off offset:2048
	global_load_dwordx4 v[34:37], v[24:25], off offset:2048
	s_waitcnt vmcnt(2)
	v_pk_mul_f32 v[0:1], v[0:1], v[30:31]
	v_pk_mul_f32 v[2:3], v[2:3], v[28:29]
	s_waitcnt vmcnt(1)
	v_pk_add_f32 v[6:7], v[6:7], 1.0 op_sel_hi:[1,0]
	v_pk_add_f32 v[4:5], v[4:5], 1.0 op_sel_hi:[1,0]
	s_waitcnt vmcnt(0)
	v_pk_fma_f32 v[2:3], v[6:7], v[2:3], v[36:37]
	v_pk_fma_f32 v[0:1], v[4:5], v[0:1], v[34:35]
	v_bfe_u32 v6, v2, 16, 1
	v_bfe_u32 v4, v0, 16, 1
	v_bfe_u32 v5, v1, 16, 1
	v_bfe_u32 v7, v3, 16, 1
	v_add3_u32 v0, v0, v4, s18
	v_add3_u32 v2, v2, v6, s18
	v_add3_u32 v1, v1, v5, s18
	v_add3_u32 v3, v3, v7, s18
	v_lshrrev_b32_e32 v0, 16, v0
	v_lshrrev_b32_e32 v2, 16, v2
	v_and_or_b32 v0, v1, s19, v0
	v_and_or_b32 v1, v3, s19, v2
	global_store_dwordx2 v[26:27], v[0:1], off offset:1024
	global_load_dwordx4 v[0:3], v[16:17], off offset:3072
	s_nop 0
	global_load_dwordx4 v[4:7], v[22:23], off offset:3072
	global_load_dwordx4 v[28:31], v[24:25], off offset:3072
	s_waitcnt vmcnt(2)
	v_pk_mul_f32 v[0:1], v[8:9], v[0:1]
	v_pk_mul_f32 v[2:3], v[10:11], v[2:3]
	s_waitcnt vmcnt(1)
	v_pk_add_f32 v[6:7], v[6:7], 1.0 op_sel_hi:[1,0]
	v_pk_add_f32 v[4:5], v[4:5], 1.0 op_sel_hi:[1,0]
	s_waitcnt vmcnt(0)
	v_pk_fma_f32 v[2:3], v[2:3], v[6:7], v[30:31]
	v_pk_fma_f32 v[0:1], v[0:1], v[4:5], v[28:29]
	v_bfe_u32 v6, v2, 16, 1
	v_bfe_u32 v4, v0, 16, 1
	v_bfe_u32 v5, v1, 16, 1
	v_bfe_u32 v7, v3, 16, 1
	v_add3_u32 v0, v0, v4, s18
	v_add3_u32 v2, v2, v6, s18
	v_add3_u32 v1, v1, v5, s18
	v_add3_u32 v3, v3, v7, s18
	v_lshrrev_b32_e32 v0, 16, v0
	v_lshrrev_b32_e32 v2, 16, v2
	v_and_or_b32 v0, v1, s19, v0
	v_and_or_b32 v1, v3, s19, v2
	global_store_dwordx2 v[26:27], v[0:1], off offset:1536
	s_cbranch_scc0 .LBB0_83
	s_add_i32 s1, s1, s0
	s_add_i32 s3, s3, s16
	s_cmpk_gt_i32 s1, 0xff
	s_cbranch_scc0 .LBB0_82

; __device__ __forceinline__ float silu_f(float x) { return x / (1.0f + __expf(-x)); }
; __device__ __forceinline__ void mod_phase(int j0, int j1, LAS unsigned char* lds, int vcu, int G, int tid, int wave, int lane) {
;     ...
;     for (int job = j0 + vcu; job < j1; job += G) {
;         const int lm = job / 144, colbase = (job % 144) * 64, kk = lane >> 4, c4 = lane & 15;
;         f32x4 acc0 = {0.f, 0.f, 0.f, 0.f}, acc1 = {0.f, 0.f, 0.f, 0.f};
;         const float* wp = w_ada + ((size_t)lm * 1024 + wave * 128 + kk) * 9216 + colbase + 4 * c4;
; #pragma unroll 8
;         for (int i = 0; i < 32; ++i) { const int k = wave * 128 + 4 * i + kk; const f32x4 wv = *(const f32x4*)(wp + (size_t)i * 4 * 9216); const float a0 = silu_f(c[k]), a1 = silu_f(c[1024 + k]); acc0 += a0 * wv; acc1 += a1 * wv; }
.LBB0_89:
	v_add_co_u32_e64 v4, s[8:9], s40, v40
	v_add_u32_e32 v34, s57, v66
	s_nop 0
	v_addc_co_u32_e64 v5, s[8:9], -1, v41, s[8:9]
	v_add_co_u32_e64 v6, s[8:9], s41, v40
	v_add_co_u32_e32 v28, vcc, 0xfff70000, v40
	s_nop 0
	v_addc_co_u32_e64 v7, s[8:9], -1, v41, s[8:9]
	v_add_co_u32_e64 v30, s[8:9], s52, v40
	v_addc_co_u32_e32 v29, vcc, -1, v41, vcc
	s_nop 0
	v_addc_co_u32_e64 v31, s[8:9], -1, v41, s[8:9]
	v_add_co_u32_e64 v68, s[8:9], s53, v40
	v_lshl_add_u64 v[74:75], v[34:35], 2, s[44:45]
	s_nop 0
	v_addc_co_u32_e64 v69, s[8:9], 0, v41, s[8:9]
	v_add_co_u32_e64 v70, s[8:9], s54, v40
	v_mov_b32_e32 v51, v35
	s_nop 0
	v_addc_co_u32_e64 v71, s[8:9], 0, v41, s[8:9]
	v_add_co_u32_e64 v72, s[8:9], s55, v40
	global_load_dwordx4 v[0:3], v[40:41], off nt
	s_nop 0
	v_addc_co_u32_e64 v73, s[8:9], 0, v41, s[8:9]
	v_add_u32_e32 v50, 4, v34
	global_load_dwordx4 v[24:27], v[4:5], off nt
	global_load_dwordx4 v[20:23], v[6:7], off nt
	global_load_dwordx4 v[16:19], v[30:31], off nt
	global_load_dwordx4 v[12:15], v[68:69], off nt
	global_load_dwordx4 v[8:11], v[70:71], off nt
	s_nop 0
	global_load_dwordx4 v[4:7], v[72:73], off nt
	v_add_co_u32_e32 v68, vcc, s33, v74
	v_add_u32_e32 v52, 8, v34
	v_add_u32_e32 v54, 12, v34
	v_add_u32_e32 v56, 16, v34
	v_add_u32_e32 v58, 20, v34
	v_add_u32_e32 v60, 24, v34
	v_add_u32_e32 v34, 28, v34
	v_addc_co_u32_e32 v69, vcc, 0, v75, vcc
	v_lshl_add_u64 v[50:51], v[50:51], 2, s[44:45]
	v_mov_b32_e32 v53, v35
	v_mov_b32_e32 v55, v35
	v_mov_b32_e32 v59, v35
	v_mov_b32_e32 v61, v35
	global_load_dwordx4 v[28:31], v[28:29], off nt
	v_lshl_add_u64 v[70:71], v[34:35], 2, s[44:45]
	global_load_dword v34, v[74:75], off
	global_load_dword v39, v[68:69], off
	global_load_dword v67, v[50:51], off
	v_add_co_u32_e32 v50, vcc, s33, v50
	v_lshl_add_u64 v[52:53], v[52:53], 2, s[44:45]
	v_lshl_add_u64 v[54:55], v[54:55], 2, s[44:45]
	v_lshl_add_u64 v[58:59], v[58:59], 2, s[44:45]
	v_lshl_add_u64 v[60:61], v[60:61], 2, s[44:45]
	v_addc_co_u32_e32 v51, vcc, 0, v51, vcc
	global_load_dword v72, v[52:53], off
	global_load_dword v73, v[54:55], off
	global_load_dword v74, v[58:59], off
	global_load_dword v75, v[60:61], off
	global_load_dword v77, v[70:71], off
	v_add_co_u32_e32 v52, vcc, s33, v52
	v_mov_b32_e32 v57, v35
	s_nop 0
	v_addc_co_u32_e32 v53, vcc, 0, v53, vcc
	v_add_co_u32_e32 v54, vcc, s33, v54
	v_lshl_add_u64 v[56:57], v[56:57], 2, s[44:45]
	s_nop 0
	v_addc_co_u32_e32 v55, vcc, 0, v55, vcc
	v_add_co_u32_e32 v68, vcc, s33, v56
	s_add_i32 s57, s57, 32
	s_nop 0
	v_addc_co_u32_e32 v69, vcc, 0, v57, vcc
	v_add_co_u32_e32 v58, vcc, s33, v58
	v_lshl_add_u64 v[40:41], v[40:41], 0, s[48:49]
	s_nop 0
	v_addc_co_u32_e32 v59, vcc, 0, v59, vcc
	v_add_co_u32_e32 v60, vcc, s33, v60
	s_cmpk_lg_i32 s57, 0x80
	s_nop 0
	v_addc_co_u32_e32 v61, vcc, 0, v61, vcc
	v_add_co_u32_e32 v70, vcc, s33, v70
	s_nop 1
	v_addc_co_u32_e32 v71, vcc, 0, v71, vcc
	global_load_dword v78, v[50:51], off
	global_load_dword v79, v[52:53], off
	global_load_dword v80, v[54:55], off
	global_load_dword v81, v[56:57], off
	global_load_dword v82, v[68:69], off
	global_load_dword v83, v[58:59], off
	global_load_dword v84, v[60:61], off
	global_load_dword v85, v[70:71], off
	s_waitcnt vmcnt(15)
	v_mul_f32_e32 v50, 0xbfb8aa3b, v34
	v_exp_f32_e32 v50, v50
	s_waitcnt vmcnt(14)
	v_mul_f32_e32 v51, 0xbfb8aa3b, v39
	s_waitcnt vmcnt(13)
	v_mul_f32_e32 v52, 0xbfb8aa3b, v67
	v_exp_f32_e32 v51, v51
	v_exp_f32_e32 v52, v52
	v_add_f32_e32 v50, 1.0, v50
	v_div_scale_f32 v86, s[8:9], v50, v50, v34
	v_add_f32_e32 v51, 1.0, v51
	v_add_f32_e32 v52, 1.0, v52
	s_waitcnt vmcnt(12)
	v_mul_f32_e32 v53, 0xbfb8aa3b, v72
	v_exp_f32_e32 v53, v53
	s_waitcnt vmcnt(11)
	v_mul_f32_e32 v54, 0xbfb8aa3b, v73
	s_waitcnt vmcnt(9)
	v_mul_f32_e32 v56, 0xbfb8aa3b, v75
	s_waitcnt vmcnt(8)
	v_mul_f32_e32 v57, 0xbfb8aa3b, v77
	v_exp_f32_e32 v56, v56
	v_exp_f32_e32 v57, v57
	v_exp_f32_e32 v54, v54
	v_rcp_f32_e32 v88, v86
	v_add_f32_e32 v56, 1.0, v56
	v_div_scale_f32 v89, s[8:9], v51, v51, v39
	v_add_f32_e32 v57, 1.0, v57
	v_div_scale_f32 v91, s[8:9], v52, v52, v67
	v_div_scale_f32 v99, s[8:9], v56, v56, v75
	v_rcp_f32_e32 v103, v89
	v_add_f32_e32 v53, 1.0, v53
	v_div_scale_f32 v101, s[8:9], v57, v57, v77
	v_rcp_f32_e32 v104, v91
	v_rcp_f32_e32 v120, v99
	v_mul_f32_e32 v55, 0xbfb8aa3b, v74
	v_div_scale_f32 v93, s[8:9], v53, v53, v72
	v_rcp_f32_e32 v123, v101
	v_exp_f32_e32 v55, v55
	s_waitcnt vmcnt(7)
	v_mul_f32_e32 v58, 0xbfb8aa3b, v78
	v_exp_f32_e32 v58, v58
	s_waitcnt vmcnt(6)
	v_mul_f32_e32 v59, 0xbfb8aa3b, v79
	v_exp_f32_e32 v59, v59
	s_waitcnt vmcnt(3)
	v_mul_f32_e32 v68, 0xbfb8aa3b, v82
	v_exp_f32_e32 v68, v68
	s_waitcnt vmcnt(1)
	v_mul_f32_e32 v70, 0xbfb8aa3b, v84
	s_waitcnt vmcnt(0)
; __device__ __forceinline__ float silu_f(float x) { return x / (1.0f + __expf(-x)); }
; __device__ __forceinline__ void mod_phase(int j0, int j1, LAS unsigned char* lds, int vcu, int G, int tid, int wave, int lane) {
;     ...
;         for (int i = 0; i < 32; ++i) { const int k = wave * 128 + 4 * i + kk; const f32x4 wv = *(const f32x4*)(wp + (size_t)i * 4 * 9216); const float a0 = silu_f(c[k]), a1 = silu_f(c[1024 + k]); acc0 += a0 * wv; acc1 += a1 * wv; }
	v_mul_f32_e32 v71, 0xbfb8aa3b, v85
	v_exp_f32_e32 v70, v70
	v_exp_f32_e32 v71, v71
	v_mul_f32_e32 v60, 0xbfb8aa3b, v80
	v_mul_f32_e32 v61, 0xbfb8aa3b, v81
	v_exp_f32_e32 v60, v60
	v_add_f32_e32 v58, 1.0, v58
	v_add_f32_e32 v70, 1.0, v70
	v_exp_f32_e32 v61, v61
	v_add_f32_e32 v68, 1.0, v68
	v_add_f32_e32 v71, 1.0, v71
	v_div_scale_f32 v105, s[14:15], v58, v58, v78
	v_div_scale_f32 v121, s[14:15], v70, v70, v84
	v_add_f32_e32 v59, 1.0, v59
	v_div_scale_f32 v115, s[14:15], v68, v68, v82
	v_div_scale_f32 v124, s[14:15], v71, v71, v85
	v_rcp_f32_e32 v126, v105
	v_rcp_f32_e32 v132, v121
	v_mul_f32_e32 v69, 0xbfb8aa3b, v83
	v_add_f32_e32 v54, 1.0, v54
	v_rcp_f32_e32 v107, v93
	v_div_scale_f32 v108, s[14:15], v59, v59, v79
	v_rcp_f32_e32 v130, v115
	v_rcp_f32_e32 v133, v124
	v_fma_f32 v134, -v86, v88, 1.0
	v_exp_f32_e32 v69, v69
	v_div_scale_f32 v87, vcc, v34, v50, v34
	v_div_scale_f32 v95, s[8:9], v54, v54, v73
	v_add_f32_e32 v60, 1.0, v60
	v_rcp_f32_e32 v127, v108
	v_fmac_f32_e32 v88, v134, v88
	v_fma_f32 v134, -v89, v103, 1.0
	v_div_scale_f32 v90, s[36:37], v39, v51, v39
	v_add_f32_e32 v61, 1.0, v61
	v_rcp_f32_e32 v110, v95
	v_div_scale_f32 v111, s[14:15], v60, v60, v80
	v_fma_f32 v135, -v91, v104, 1.0
	v_fma_f32 v139, -v99, v120, 1.0
	v_mul_f32_e32 v141, v87, v88
	v_fmac_f32_e32 v103, v134, v103
	v_div_scale_f32 v92, s[26:27], v67, v52, v67
	v_div_scale_f32 v113, s[14:15], v61, v61, v81
	v_rcp_f32_e32 v128, v111
	v_fma_f32 v140, -v101, v123, 1.0
	v_fmac_f32_e32 v104, v135, v104
	v_fma_f32 v134, -v105, v126, 1.0
	v_fmac_f32_e32 v120, v139, v120
	v_fma_f32 v139, -v121, v132, 1.0
	v_fma_f32 v143, -v86, v141, v87
	v_mul_f32_e32 v144, v90, v103
	v_add_f32_e32 v55, 1.0, v55
	v_div_scale_f32 v106, s[38:39], v78, v58, v78
	v_rcp_f32_e32 v129, v113
	v_fma_f32 v136, -v93, v107, 1.0
	v_fma_f32 v142, -v115, v130, 1.0
	v_fmac_f32_e32 v123, v140, v123
	v_fma_f32 v140, -v124, v133, 1.0
	v_mul_f32_e32 v145, v92, v104
	v_fmac_f32_e32 v126, v134, v126
	v_fmac_f32_e32 v132, v139, v132
	v_fmac_f32_e32 v141, v143, v88
	v_fma_f32 v139, -v89, v144, v90
	v_div_scale_f32 v94, s[22:23], v72, v53, v72
	v_div_scale_f32 v97, s[8:9], v55, v55, v74
	v_add_f32_e32 v69, 1.0, v69
	v_fmac_f32_e32 v107, v136, v107
	v_fma_f32 v135, -v108, v127, 1.0
	v_fmac_f32_e32 v130, v142, v130
	v_fmac_f32_e32 v133, v140, v133
	v_fma_f32 v140, -v91, v145, v92
	v_mul_f32_e32 v142, v106, v126
	v_fma_f32 v86, -v86, v141, v87
	v_fmac_f32_e32 v144, v139, v103
	v_div_scale_f32 v109, s[34:35], v79, v59, v79
	v_rcp_f32_e32 v117, v97
	v_div_scale_f32 v118, s[14:15], v69, v69, v83
	v_fma_f32 v137, -v95, v110, 1.0
	v_mul_f32_e32 v134, v94, v107
	v_fmac_f32_e32 v127, v135, v127
	v_fmac_f32_e32 v145, v140, v104
	v_fma_f32 v87, -v105, v142, v106
	v_div_fmas_f32 v86, v86, v88, v141
	v_fma_f32 v88, -v89, v144, v90
	s_mov_b64 vcc, s[36:37]
	v_div_scale_f32 v96, s[18:19], v73, v54, v73
	v_rcp_f32_e32 v131, v118
	v_fmac_f32_e32 v110, v137, v110
	v_fma_f32 v136, -v111, v128, 1.0
	v_fma_f32 v143, -v93, v134, v94
	v_mul_f32_e32 v146, v109, v127
	v_fma_f32 v89, -v91, v145, v92
	v_fmac_f32_e32 v142, v87, v126
	v_div_fmas_f32 v88, v88, v103, v144
	v_div_fixup_f32 v34, v86, v50, v34
	s_mov_b64 vcc, s[26:27]
	v_div_scale_f32 v112, s[30:31], v80, v60, v80
	v_fma_f32 v137, -v113, v129, 1.0
	v_mul_f32_e32 v135, v96, v110
	v_fmac_f32_e32 v128, v136, v128
	v_fmac_f32_e32 v134, v143, v107
	v_fma_f32 v139, -v108, v146, v109
	v_fma_f32 v50, -v105, v142, v106
	v_pk_fma_f32 v[48:49], v[28:29], v[34:35], v[48:49] op_sel_hi:[1,0,1]
	v_pk_fma_f32 v[44:45], v[30:31], v[34:35], v[44:45] op_sel_hi:[1,0,1]
	v_div_fixup_f32 v34, v88, v51, v39
	v_div_fmas_f32 v39, v89, v104, v145
	s_mov_b64 vcc, s[38:39]
	v_div_scale_f32 v114, s[28:29], v81, v61, v81
	v_fmac_f32_e32 v129, v137, v129
	v_fma_f32 v147, -v95, v135, v96
	v_mul_f32_e32 v148, v112, v128
	v_fma_f32 v87, -v93, v134, v94
	v_fmac_f32_e32 v146, v139, v127
	v_pk_fma_f32 v[28:29], v[28:29], v[34:35], v[46:47] op_sel_hi:[1,0,1]
	v_pk_fma_f32 v[30:31], v[30:31], v[34:35], v[42:43] op_sel_hi:[1,0,1]
	v_div_fmas_f32 v46, v50, v126, v142
	v_div_fixup_f32 v34, v39, v52, v67
	s_mov_b64 vcc, s[22:23]
	v_div_scale_f32 v116, s[24:25], v82, v68, v82
	v_fma_f32 v138, -v97, v117, 1.0
	v_mul_f32_e32 v149, v114, v129
	v_fmac_f32_e32 v135, v147, v110
	v_fma_f32 v140, -v111, v148, v112
	v_fma_f32 v86, -v108, v146, v109
	v_pk_fma_f32 v[42:43], v[26:27], v[34:35], v[44:45] op_sel_hi:[1,0,1]
	v_pk_fma_f32 v[44:45], v[24:25], v[34:35], v[48:49] op_sel_hi:[1,0,1]
	v_div_fixup_f32 v34, v46, v58, v78
	v_div_fmas_f32 v39, v87, v107, v134
	s_mov_b64 vcc, s[34:35]
	v_div_scale_f32 v98, s[12:13], v74, v55, v74
	v_fmac_f32_e32 v117, v138, v117
	v_fma_f32 v138, -v118, v131, 1.0
	v_mul_f32_e32 v153, v116, v130
	v_fma_f32 v143, -v113, v149, v114
	v_fma_f32 v90, -v95, v135, v96
	v_fmac_f32_e32 v148, v140, v128
	v_pk_fma_f32 v[26:27], v[26:27], v[34:35], v[30:31] op_sel_hi:[1,0,1]
	v_pk_fma_f32 v[24:25], v[24:25], v[34:35], v[28:29] op_sel_hi:[1,0,1]
	v_div_fmas_f32 v34, v86, v127, v146
	s_mov_b64 vcc, s[18:19]
; #define LAS __attribute__((address_space(3)))
; __device__ __forceinline__ float silu_f(float x) { return x / (1.0f + __expf(-x)); }
; __device__ __forceinline__ void mod_phase(int j0, int j1, LAS unsigned char* lds, int vcu, int G, int tid, int wave, int lane) {
;     ...
;         for (int i = 0; i < 32; ++i) { const int k = wave * 128 + 4 * i + kk; const f32x4 wv = *(const f32x4*)(wp + (size_t)i * 4 * 9216); const float a0 = silu_f(c[k]), a1 = silu_f(c[1024 + k]); acc0 += a0 * wv; acc1 += a1 * wv; }
; #pragma unroll
;         for (int e = 0; e < 4; ++e) { acc0[e] += __shfl_xor(acc0[e], 16); acc0[e] += __shfl_xor(acc0[e], 32); acc1[e] += __shfl_xor(acc1[e], 16); acc1[e] += __shfl_xor(acc1[e], 32); }
;         if (kk == 0) { *(LAS f32x4*)(part + (wave * 2 + 0) * 64 + 4 * c4) = acc0; *(LAS f32x4*)(part + (wave * 2 + 1) * 64 + 4 * c4) = acc1; }
	v_div_scale_f32 v119, s[20:21], v83, v69, v83
	v_mul_f32_e32 v136, v98, v117
	v_fmac_f32_e32 v131, v138, v131
	v_fma_f32 v147, -v115, v153, v116
	v_fmac_f32_e32 v149, v143, v129
	v_fma_f32 v94, -v111, v148, v112
	v_div_fixup_f32 v28, v39, v53, v72
	v_div_fixup_f32 v34, v34, v59, v79
	v_div_fmas_f32 v39, v90, v110, v135
	s_mov_b64 vcc, s[30:31]
	v_div_scale_f32 v100, s[10:11], v75, v56, v75
	v_fma_f32 v150, -v97, v136, v98
	v_mul_f32_e32 v154, v119, v131
	v_fmac_f32_e32 v153, v147, v130
	v_fma_f32 v95, -v113, v149, v114
	v_pk_fma_f32 v[30:31], v[20:21], v[28:29], v[44:45] op_sel_hi:[1,0,1]
	v_pk_fma_f32 v[28:29], v[22:23], v[28:29], v[42:43] op_sel_hi:[1,0,1]
	v_pk_fma_f32 v[20:21], v[20:21], v[34:35], v[24:25] op_sel_hi:[1,0,1]
	v_pk_fma_f32 v[22:23], v[22:23], v[34:35], v[26:27] op_sel_hi:[1,0,1]
	v_div_fixup_f32 v24, v39, v54, v73
	v_div_fmas_f32 v34, v94, v128, v148
	s_mov_b64 vcc, s[28:29]
	v_div_scale_f32 v122, s[16:17], v84, v70, v84
	v_mul_f32_e32 v137, v100, v120
	v_fmac_f32_e32 v136, v150, v117
	v_fma_f32 v150, -v118, v154, v119
	v_fma_f32 v96, -v115, v153, v116
	v_pk_fma_f32 v[26:27], v[18:19], v[24:25], v[28:29] op_sel_hi:[1,0,1]
	v_div_fixup_f32 v28, v34, v60, v80
	v_div_fmas_f32 v29, v95, v129, v149
	s_mov_b64 vcc, s[24:25]
	v_div_scale_f32 v102, s[8:9], v77, v57, v77
	v_fma_f32 v151, -v99, v137, v100
	v_mul_f32_e32 v155, v122, v132
	v_fma_f32 v91, -v97, v136, v98
	v_fmac_f32_e32 v154, v150, v131
	v_pk_fma_f32 v[24:25], v[16:17], v[24:25], v[30:31] op_sel_hi:[1,0,1]
	v_pk_fma_f32 v[16:17], v[16:17], v[28:29], v[20:21] op_sel_hi:[1,0,1]
	v_div_fmas_f32 v21, v96, v130, v153
	s_mov_b64 vcc, s[12:13]
	v_div_scale_f32 v125, s[14:15], v85, v71, v85
	v_mul_f32_e32 v138, v102, v123
	v_fmac_f32_e32 v137, v151, v120
	v_fma_f32 v151, -v121, v155, v122
	v_fma_f32 v97, -v118, v154, v119
	v_pk_fma_f32 v[18:19], v[18:19], v[28:29], v[22:23] op_sel_hi:[1,0,1]
	v_div_fixup_f32 v20, v29, v61, v81
	v_div_fixup_f32 v22, v21, v68, v82
	v_div_fmas_f32 v23, v91, v117, v136
	s_mov_b64 vcc, s[20:21]
	v_fma_f32 v152, -v101, v138, v102
	v_mul_f32_e32 v156, v125, v133
	v_fma_f32 v92, -v99, v137, v100
	v_fmac_f32_e32 v155, v151, v132
	v_pk_fma_f32 v[24:25], v[0:1], v[20:21], v[24:25] op_sel_hi:[1,0,1]
	v_pk_fma_f32 v[0:1], v[0:1], v[22:23], v[16:17] op_sel_hi:[1,0,1]
	v_div_fmas_f32 v17, v97, v131, v154
	s_mov_b64 vcc, s[10:11]
	v_fmac_f32_e32 v138, v152, v123
	v_fma_f32 v152, -v124, v156, v125
	v_fma_f32 v98, -v121, v155, v122
	v_pk_fma_f32 v[20:21], v[2:3], v[20:21], v[26:27] op_sel_hi:[1,0,1]
	v_pk_fma_f32 v[2:3], v[2:3], v[22:23], v[18:19] op_sel_hi:[1,0,1]
	v_div_fixup_f32 v16, v23, v55, v74
	v_div_fixup_f32 v18, v17, v69, v83
	v_div_fmas_f32 v19, v92, v120, v137
	s_mov_b64 vcc, s[16:17]
	v_fma_f32 v93, -v101, v138, v102
	v_fmac_f32_e32 v156, v152, v133
	v_pk_fma_f32 v[20:21], v[14:15], v[16:17], v[20:21] op_sel_hi:[1,0,1]
	v_pk_fma_f32 v[16:17], v[12:13], v[16:17], v[24:25] op_sel_hi:[1,0,1]
	v_pk_fma_f32 v[0:1], v[12:13], v[18:19], v[0:1] op_sel_hi:[1,0,1]
	v_div_fmas_f32 v13, v98, v132, v155
	s_mov_b64 vcc, s[8:9]
	v_fma_f32 v99, -v124, v156, v125
	v_pk_fma_f32 v[2:3], v[14:15], v[18:19], v[2:3] op_sel_hi:[1,0,1]
	v_div_fixup_f32 v12, v19, v56, v75
	v_div_fixup_f32 v14, v13, v70, v84
	v_div_fmas_f32 v15, v93, v123, v138
	s_mov_b64 vcc, s[14:15]
	v_pk_fma_f32 v[16:17], v[8:9], v[12:13], v[16:17] op_sel_hi:[1,0,1]
	v_pk_fma_f32 v[0:1], v[8:9], v[14:15], v[0:1] op_sel_hi:[1,0,1]
	v_div_fmas_f32 v9, v99, v133, v156
	v_pk_fma_f32 v[12:13], v[10:11], v[12:13], v[20:21] op_sel_hi:[1,0,1]
	v_pk_fma_f32 v[2:3], v[10:11], v[14:15], v[2:3] op_sel_hi:[1,0,1]
	v_div_fixup_f32 v8, v15, v57, v77
	v_div_fixup_f32 v10, v9, v71, v85
	v_pk_fma_f32 v[44:45], v[6:7], v[8:9], v[12:13] op_sel_hi:[1,0,1]
	v_pk_fma_f32 v[48:49], v[4:5], v[8:9], v[16:17] op_sel_hi:[1,0,1]
	v_pk_fma_f32 v[42:43], v[6:7], v[10:11], v[2:3] op_sel_hi:[1,0,1]
	v_pk_fma_f32 v[46:47], v[4:5], v[10:11], v[0:1] op_sel_hi:[1,0,1]
	s_cbranch_scc1 .LBB0_89
	ds_bpermute_b32 v0, v33, v48
	ds_bpermute_b32 v1, v33, v49
	ds_bpermute_b32 v4, v33, v46
	ds_bpermute_b32 v5, v33, v47
	ds_bpermute_b32 v8, v33, v44
	ds_bpermute_b32 v9, v33, v45
	ds_bpermute_b32 v12, v33, v42
	ds_bpermute_b32 v13, v33, v43
	s_waitcnt lgkmcnt(6)
	v_pk_add_f32 v[0:1], v[48:49], v[0:1]
	s_waitcnt lgkmcnt(4)
	v_pk_add_f32 v[4:5], v[46:47], v[4:5]
	s_waitcnt lgkmcnt(2)
	v_pk_add_f32 v[8:9], v[44:45], v[8:9]
	ds_bpermute_b32 v2, v62, v0
	s_waitcnt lgkmcnt(1)
	v_pk_add_f32 v[12:13], v[42:43], v[12:13]
	ds_bpermute_b32 v3, v62, v1
	ds_bpermute_b32 v6, v62, v4
	ds_bpermute_b32 v7, v62, v5
	ds_bpermute_b32 v10, v62, v8
	ds_bpermute_b32 v11, v62, v9
	ds_bpermute_b32 v14, v62, v12
	ds_bpermute_b32 v15, v62, v13
	s_and_saveexec_b64 s[8:9], s[4:5]
	s_cbranch_execz .LBB0_92
	s_waitcnt lgkmcnt(0)
	v_pk_add_f32 v[14:15], v[12:13], v[14:15]
	v_pk_add_f32 v[12:13], v[4:5], v[6:7]
	v_pk_add_f32 v[4:5], v[8:9], v[10:11]
	v_pk_add_f32 v[2:3], v[0:1], v[2:3]
	ds_write_b128 v63, v[2:5]
	ds_write_b128 v63, v[12:15] offset:256

;     __device__ __forceinline__ void fused(f32x4 (&acc)[2][2][4][2], const Unit& u, int wr, int wc, int fr, int fq, PG8_LAS unsigned char* lds, int wid, int lane) const {
;         const int row0 = u.pm * BM + wr * 64 + fr, col0 = u.pn * BM + wc * 32 + 4 * fq; const int bo = (u.pm >= 32 ? 9216 : 0); const float* gp = gate + bo + col0;
;         f32x4 gv[2][2];
; #pragma unroll
;         for (int bj = 0; bj < 2; ++bj)
; #pragma unroll
;             for (int n = 0; n < 2; ++n) gv[bj][n] = *(const f32x4*)(gp + bj * HALF + n * 16) * coef;
; #pragma unroll
;         for (int ai = 0; ai < 2; ++ai)
; #pragma unroll
;             for (int m = 0; m < 4; ++m) { const size_t off = (size_t)(row0 + ai * HALF + m * 16) * 1024 + col0;
; #pragma unroll
;                 for (int bj = 0; bj < 2; ++bj)
; #pragma unroll
;                     for (int n = 0; n < 2; ++n) { const f32x4 bs = *(const f32x4*)(base + off + bj * HALF + n * 16); acc[ai][bj][m][n] = bs + gv[bj][n] * acc[ai][bj][m][n]; *(f32x4*)(out + off + bj * HALF + n * 16) = acc[ai][bj][m][n]; }
.LBB0_387:
	v_readlane_b32 s0, v255, 17
	v_readlane_b32 s1, v255, 18
	s_and_b64 s[4:5], s[0:1], s[12:13]
	v_readlane_b32 s0, v255, 13
	s_or_b32 s0, s3, s0
	s_cmp_eq_u32 s0, 0
	v_readlane_b32 s0, v255, 21
	v_readlane_b32 s1, v255, 22
	s_cselect_b32 s7, s23, s21
	s_cselect_b32 s6, s22, s20
	s_lshl_b64 s[0:1], s[0:1], 2
	s_add_u32 s8, s14, s0
	s_addc_u32 s9, s15, s1
	s_and_b64 s[0:1], s[12:13], exec
	s_movk_i32 s0, 0x2000
	s_cselect_b32 s0, 0x8000, s0
	s_add_u32 s8, s8, s0
	s_addc_u32 s9, s9, 0
	s_lshl_b32 s1, s38, 5
	s_lshl_b32 s0, s37, 8
	s_lshl_b32 s23, s18, 8
	s_add_i32 s22, s0, s49
	s_or_b32 s1, s23, s1
	v_lshrrev_b32_e32 v0, 2, v153
	s_cmp_gt_i32 s37, 31
	v_and_or_b32 v140, v0, 12, s1
	s_cselect_b32 s1, 0x2400, 0
	s_lshl_b32 s1, s1, 2
	s_add_u32 s8, s8, s1
	s_addc_u32 s9, s9, 0
	v_ashrrev_i32_e32 v141, 31, v140
	v_lshl_add_u64 v[150:151], v[140:141], 2, s[8:9]
	s_barrier
	global_load_dwordx4 v[130:133], v[150:151], off
	global_load_dwordx4 v[154:157], v[150:151], off offset:576
	s_mov_b64 s[8:9], 0x80000
	s_and_b64 vcc, exec, s[4:5]
	s_movk_i32 s58, 0x7fff
	s_mov_b32 s59, 0xffff0000
	s_mov_b64 s[60:61], 0x1000
	s_waitcnt vmcnt(0)
	v_pk_mul_f32 v[144:145], v[132:133], 0.5 op_sel_hi:[1,0]
	v_pk_mul_f32 v[146:147], v[130:131], 0.5 op_sel_hi:[1,0]
	global_load_dwordx4 v[130:133], v[150:151], off offset:64
	s_waitcnt vmcnt(0)
	v_pk_mul_f32 v[138:139], v[132:133], 0.5 op_sel_hi:[1,0]
	v_pk_mul_f32 v[142:143], v[130:131], 0.5 op_sel_hi:[1,0]
	global_load_dwordx4 v[130:133], v[150:151], off offset:512
	v_or_b32_e32 v150, s22, v148
	v_ashrrev_i32_e32 v151, 31, v150
	v_lshlrev_b64 v[148:149], 10, v[150:151]
	v_lshl_add_u64 v[148:149], v[148:149], 0, v[140:141]
	v_lshlrev_b64 v[148:149], 2, v[148:149]
	v_lshl_add_u64 v[158:159], s[6:7], 0, v[148:149]
	v_lshl_add_u64 v[160:161], s[20:21], 0, v[148:149]
	s_waitcnt vmcnt(0)
	v_pk_mul_f32 v[134:135], v[132:133], 0.5 op_sel_hi:[1,0]
	v_pk_mul_f32 v[136:137], v[130:131], 0.5 op_sel_hi:[1,0]
	v_pk_mul_f32 v[130:131], v[156:157], 0.5 op_sel_hi:[1,0]
	v_pk_mul_f32 v[132:133], v[154:155], 0.5 op_sel_hi:[1,0]
	global_load_dwordx4 v[170:173], v[158:159], off nt
	global_load_dwordx4 v[174:177], v[158:159], off offset:64 nt
	global_load_dwordx4 v[178:181], v[158:159], off offset:512 nt
	global_load_dwordx4 v[182:185], v[158:159], off offset:576 nt
	s_waitcnt vmcnt(3)
	v_pk_fma_f32 v[116:117], v[116:117], v[144:145], v[172:173]
	v_pk_fma_f32 v[114:115], v[114:115], v[146:147], v[170:171]
	global_store_dwordx4 v[160:161], v[114:117], off
	s_waitcnt vmcnt(3)
	v_pk_fma_f32 v[84:85], v[84:85], v[138:139], v[176:177]
	v_pk_fma_f32 v[82:83], v[82:83], v[142:143], v[174:175]
	global_store_dwordx4 v[160:161], v[82:85], off offset:64
	s_waitcnt vmcnt(3)
	v_pk_fma_f32 v[28:29], v[28:29], v[134:135], v[180:181]
	v_pk_fma_f32 v[26:27], v[26:27], v[136:137], v[178:179]
	global_store_dwordx4 v[160:161], v[26:29], off offset:512
	s_waitcnt vmcnt(3)
	v_pk_fma_f32 v[2:3], v[2:3], v[132:133], v[182:183]
	v_or_b32_e32 v154, 16, v150
	v_ashrrev_i32_e32 v155, 31, v154
	v_lshlrev_b64 v[154:155], 10, v[154:155]
	v_lshl_add_u64 v[154:155], v[154:155], 0, v[140:141]
	v_pk_fma_f32 v[4:5], v[4:5], v[130:131], v[184:185]
	v_lshlrev_b64 v[158:159], 2, v[154:155]
	global_store_dwordx4 v[160:161], v[2:5], off offset:576
	v_lshl_add_u64 v[160:161], s[6:7], 0, v[158:159]
	global_load_dwordx4 v[170:173], v[160:161], off nt
	global_load_dwordx4 v[174:177], v[160:161], off offset:64 nt
	global_load_dwordx4 v[178:181], v[160:161], off offset:512 nt
	global_load_dwordx4 v[182:185], v[160:161], off offset:576 nt
	v_lshl_add_u64 v[158:159], s[20:21], 0, v[158:159]
	s_waitcnt vmcnt(3)
	v_pk_fma_f32 v[124:125], v[124:125], v[144:145], v[172:173]
	v_pk_fma_f32 v[122:123], v[122:123], v[146:147], v[170:171]
	global_store_dwordx4 v[158:159], v[122:125], off
	s_waitcnt vmcnt(3)
	v_pk_fma_f32 v[96:97], v[96:97], v[138:139], v[176:177]
	v_pk_fma_f32 v[94:95], v[94:95], v[142:143], v[174:175]
	global_store_dwordx4 v[158:159], v[94:97], off offset:64
	s_waitcnt vmcnt(3)
	v_pk_fma_f32 v[36:37], v[36:37], v[134:135], v[180:181]
	v_pk_fma_f32 v[34:35], v[34:35], v[136:137], v[178:179]
	global_store_dwordx4 v[158:159], v[34:37], off offset:512
	s_waitcnt vmcnt(3)
	v_pk_fma_f32 v[6:7], v[6:7], v[132:133], v[182:183]
	v_or_b32_e32 v154, 32, v150
	v_ashrrev_i32_e32 v155, 31, v154
	v_lshlrev_b64 v[154:155], 10, v[154:155]
	v_pk_fma_f32 v[8:9], v[8:9], v[130:131], v[184:185]
	v_lshl_add_u64 v[154:155], v[154:155], 0, v[140:141]
	global_store_dwordx4 v[158:159], v[6:9], off offset:576
	v_lshlrev_b64 v[158:159], 2, v[154:155]
	v_lshl_add_u64 v[160:161], s[6:7], 0, v[158:159]
	global_load_dwordx4 v[170:173], v[160:161], off nt
	global_load_dwordx4 v[174:177], v[160:161], off offset:64 nt
	global_load_dwordx4 v[178:181], v[160:161], off offset:512 nt
	global_load_dwordx4 v[182:185], v[160:161], off offset:576 nt
	v_lshl_add_u64 v[158:159], s[20:21], 0, v[158:159]
	v_or_b32_e32 v150, 48, v150
	v_ashrrev_i32_e32 v151, 31, v150
	v_lshlrev_b64 v[150:151], 10, v[150:151]
	v_lshl_add_u64 v[150:151], v[150:151], 0, v[140:141]
	v_lshlrev_b64 v[150:151], 2, v[150:151]
	s_waitcnt vmcnt(3)
	v_pk_fma_f32 v[128:129], v[128:129], v[144:145], v[172:173]
	v_pk_fma_f32 v[126:127], v[126:127], v[146:147], v[170:171]
	global_store_dwordx4 v[158:159], v[126:129], off
	s_waitcnt vmcnt(3)
	v_pk_fma_f32 v[108:109], v[108:109], v[138:139], v[176:177]
	v_pk_fma_f32 v[106:107], v[106:107], v[142:143], v[174:175]
	global_store_dwordx4 v[158:159], v[106:109], off offset:64
	s_waitcnt vmcnt(3)
	v_pk_fma_f32 v[44:45], v[44:45], v[134:135], v[180:181]
	v_pk_fma_f32 v[42:43], v[42:43], v[136:137], v[178:179]
	global_store_dwordx4 v[158:159], v[42:45], off offset:512
	s_waitcnt vmcnt(3)
;     __device__ __forceinline__ void fused(f32x4 (&acc)[2][2][4][2], const Unit& u, int wr, int wc, int fr, int fq, PG8_LAS unsigned char* lds, int wid, int lane) const {
;     ...
;             for (int m = 0; m < 4; ++m) { const size_t off = (size_t)(row0 + ai * HALF + m * 16) * 1024 + col0;
; #pragma unroll
;                 for (int bj = 0; bj < 2; ++bj)
; #pragma unroll
;                     for (int n = 0; n < 2; ++n) { const f32x4 bs = *(const f32x4*)(base + off + bj * HALF + n * 16); acc[ai][bj][m][n] = bs + gv[bj][n] * acc[ai][bj][m][n]; *(f32x4*)(out + off + bj * HALF + n * 16) = acc[ai][bj][m][n]; }
;                 if (m & 1) asm volatile("" ::: "memory"); }
;         if (donorm == 0) return;
	v_pk_fma_f32 v[12:13], v[12:13], v[130:131], v[184:185]
	v_pk_fma_f32 v[10:11], v[10:11], v[132:133], v[182:183]
	global_store_dwordx4 v[158:159], v[10:13], off offset:576
	v_lshl_add_u64 v[158:159], s[6:7], 0, v[150:151]
	global_load_dwordx4 v[170:173], v[158:159], off nt
	global_load_dwordx4 v[174:177], v[158:159], off offset:64 nt
	global_load_dwordx4 v[178:181], v[158:159], off offset:512 nt
	global_load_dwordx4 v[182:185], v[158:159], off offset:576 nt
	v_lshl_add_u64 v[150:151], s[20:21], 0, v[150:151]
	s_waitcnt vmcnt(3)
	v_pk_fma_f32 v[120:121], v[120:121], v[144:145], v[172:173]
	v_pk_fma_f32 v[118:119], v[118:119], v[146:147], v[170:171]
	global_store_dwordx4 v[150:151], v[118:121], off
	s_waitcnt vmcnt(3)
	v_pk_fma_f32 v[112:113], v[112:113], v[138:139], v[176:177]
	v_pk_fma_f32 v[110:111], v[110:111], v[142:143], v[174:175]
	global_store_dwordx4 v[150:151], v[110:113], off offset:64
	s_waitcnt vmcnt(3)
	v_pk_fma_f32 v[48:49], v[48:49], v[134:135], v[180:181]
	v_pk_fma_f32 v[46:47], v[46:47], v[136:137], v[178:179]
	global_store_dwordx4 v[150:151], v[46:49], off offset:512
	s_waitcnt vmcnt(3)
	v_pk_fma_f32 v[16:17], v[16:17], v[130:131], v[184:185]
	v_pk_fma_f32 v[14:15], v[14:15], v[132:133], v[182:183]
	global_store_dwordx4 v[150:151], v[14:17], off offset:576
	v_lshl_add_u64 v[150:151], v[148:149], 0, s[8:9]
	v_lshl_add_u64 v[158:159], s[6:7], 0, v[150:151]
	global_load_dwordx4 v[170:173], v[158:159], off nt
	global_load_dwordx4 v[174:177], v[158:159], off offset:64 nt
	global_load_dwordx4 v[178:181], v[158:159], off offset:512 nt
	global_load_dwordx4 v[182:185], v[158:159], off offset:576 nt
	v_lshl_add_u64 v[150:151], s[20:21], 0, v[150:151]
	s_mov_b64 s[8:9], 0x90000
	s_waitcnt vmcnt(3)
	v_pk_fma_f32 v[104:105], v[104:105], v[144:145], v[172:173]
	v_pk_fma_f32 v[102:103], v[102:103], v[146:147], v[170:171]
	global_store_dwordx4 v[150:151], v[102:105], off
	s_waitcnt vmcnt(3)
	v_pk_fma_f32 v[100:101], v[100:101], v[138:139], v[176:177]
	v_pk_fma_f32 v[98:99], v[98:99], v[142:143], v[174:175]
	global_store_dwordx4 v[150:151], v[98:101], off offset:64
	s_waitcnt vmcnt(3)
	v_pk_fma_f32 v[56:57], v[56:57], v[134:135], v[180:181]
	v_pk_fma_f32 v[54:55], v[54:55], v[136:137], v[178:179]
	global_store_dwordx4 v[150:151], v[54:57], off offset:512
	s_waitcnt vmcnt(3)
	v_pk_fma_f32 v[20:21], v[20:21], v[130:131], v[184:185]
	v_pk_fma_f32 v[18:19], v[18:19], v[132:133], v[182:183]
	global_store_dwordx4 v[150:151], v[18:21], off offset:576
	v_lshl_add_u64 v[150:151], v[148:149], 0, s[8:9]
	v_lshl_add_u64 v[158:159], s[6:7], 0, v[150:151]
	global_load_dwordx4 v[170:173], v[158:159], off nt
	global_load_dwordx4 v[174:177], v[158:159], off offset:64 nt
	global_load_dwordx4 v[178:181], v[158:159], off offset:512 nt
	global_load_dwordx4 v[182:185], v[158:159], off offset:576 nt
	v_lshl_add_u64 v[150:151], s[20:21], 0, v[150:151]
	s_mov_b64 s[8:9], 0xa0000
	s_waitcnt vmcnt(3)
	v_pk_fma_f32 v[92:93], v[92:93], v[144:145], v[172:173]
	v_pk_fma_f32 v[90:91], v[90:91], v[146:147], v[170:171]
	global_store_dwordx4 v[150:151], v[90:93], off
	s_waitcnt vmcnt(3)
	v_pk_fma_f32 v[88:89], v[88:89], v[138:139], v[176:177]
	v_pk_fma_f32 v[86:87], v[86:87], v[142:143], v[174:175]
	global_store_dwordx4 v[150:151], v[86:89], off offset:64
	s_waitcnt vmcnt(3)
	v_pk_fma_f32 v[60:61], v[60:61], v[134:135], v[180:181]
	v_pk_fma_f32 v[58:59], v[58:59], v[136:137], v[178:179]
	global_store_dwordx4 v[150:151], v[58:61], off offset:512
	s_waitcnt vmcnt(3)
	v_pk_fma_f32 v[32:33], v[32:33], v[130:131], v[184:185]
	v_pk_fma_f32 v[30:31], v[30:31], v[132:133], v[182:183]
	global_store_dwordx4 v[150:151], v[30:33], off offset:576
	v_lshl_add_u64 v[150:151], v[148:149], 0, s[8:9]
	v_lshl_add_u64 v[158:159], s[6:7], 0, v[150:151]
	global_load_dwordx4 v[170:173], v[158:159], off nt
	global_load_dwordx4 v[174:177], v[158:159], off offset:64 nt
	global_load_dwordx4 v[178:181], v[158:159], off offset:512 nt
	global_load_dwordx4 v[182:185], v[158:159], off offset:576 nt
	v_lshl_add_u64 v[150:151], s[20:21], 0, v[150:151]
	s_mov_b64 s[8:9], 0xb0000
	s_waitcnt vmcnt(3)
	v_pk_fma_f32 v[80:81], v[80:81], v[144:145], v[172:173]
	v_pk_fma_f32 v[78:79], v[78:79], v[146:147], v[170:171]
	global_store_dwordx4 v[150:151], v[78:81], off
	s_waitcnt vmcnt(3)
	v_pk_fma_f32 v[76:77], v[76:77], v[138:139], v[176:177]
	v_pk_fma_f32 v[74:75], v[74:75], v[142:143], v[174:175]
	global_store_dwordx4 v[150:151], v[74:77], off offset:64
	s_waitcnt vmcnt(3)
	v_pk_fma_f32 v[64:65], v[64:65], v[134:135], v[180:181]
	v_pk_fma_f32 v[62:63], v[62:63], v[136:137], v[178:179]
	global_store_dwordx4 v[150:151], v[62:65], off offset:512
	s_waitcnt vmcnt(3)
	v_pk_fma_f32 v[40:41], v[40:41], v[130:131], v[184:185]
	v_pk_fma_f32 v[38:39], v[38:39], v[132:133], v[182:183]
	v_lshl_add_u64 v[154:155], v[148:149], 0, s[8:9]
	global_store_dwordx4 v[150:151], v[38:41], off offset:576
	v_lshl_add_u64 v[156:157], s[6:7], 0, v[154:155]
	global_load_dwordx4 v[170:173], v[156:157], off nt
	global_load_dwordx4 v[174:177], v[156:157], off offset:64 nt
	global_load_dwordx4 v[178:181], v[156:157], off offset:512 nt
	global_load_dwordx4 v[182:185], v[156:157], off offset:576 nt
	s_waitcnt vmcnt(3)
	v_pk_fma_f32 v[72:73], v[72:73], v[144:145], v[172:173]
	v_pk_fma_f32 v[70:71], v[70:71], v[146:147], v[170:171]
	v_lshl_add_u64 v[148:149], s[20:21], 0, v[154:155]
	global_store_dwordx4 v[148:149], v[70:73], off
	s_waitcnt vmcnt(3)
	v_pk_fma_f32 v[68:69], v[68:69], v[138:139], v[176:177]
	v_pk_fma_f32 v[66:67], v[66:67], v[142:143], v[174:175]
	global_store_dwordx4 v[148:149], v[66:69], off offset:64
	s_waitcnt vmcnt(3)
	v_pk_fma_f32 v[52:53], v[52:53], v[134:135], v[180:181]
	v_pk_fma_f32 v[50:51], v[50:51], v[136:137], v[178:179]
	global_store_dwordx4 v[148:149], v[50:53], off offset:512
	s_waitcnt vmcnt(3)
	v_pk_fma_f32 v[24:25], v[24:25], v[130:131], v[184:185]
	v_pk_fma_f32 v[22:23], v[22:23], v[132:133], v[182:183]
	global_store_dwordx4 v[148:149], v[22:25], off offset:576
	s_cbranch_vccnz .LBB0_425
;     __device__ __forceinline__ void fused(f32x4 (&acc)[2][2][4][2], const Unit& u, int wr, int wc, int fr, int fq, PG8_LAS unsigned char* lds, int wid, int lane) const {
;     ...
;             for (int m = 0; m < 4; ++m) { float q = 0.f;
; #pragma unroll
;                 for (int bj = 0; bj < 2; ++bj)
; #pragma unroll
;                     for (int n = 0; n < 2; ++n) { const f32x4 x = acc[ai][bj][m][n]; q += (x[0] * x[0] + x[1] * x[1]) + (x[2] * x[2] + x[3] * x[3]); }
;                 q += __shfl_xor(q, 16); q += __shfl_xor(q, 32);
;                 if (fq == 0) P[(ai * HALF + wr * 64 + m * 16 + fr) * 4 + wc] = q; }
	v_mul_f32_e32 v132, v115, v115
	v_mul_f32_e32 v133, v117, v117
	v_fmac_f32_e32 v132, v114, v114
	v_fmac_f32_e32 v133, v116, v116
	v_add_f32_e32 v132, v132, v133
	v_mul_f32_e32 v133, v83, v83
	v_mul_f32_e32 v134, v85, v85
	v_fmac_f32_e32 v133, v82, v82
	v_fmac_f32_e32 v134, v84, v84
	v_add_f32_e32 v133, v133, v134
	v_add_f32_e32 v132, v132, v133
	v_mul_f32_e32 v133, v27, v27
	v_mul_f32_e32 v134, v29, v29
	v_fmac_f32_e32 v133, v26, v26
	v_fmac_f32_e32 v134, v28, v28
	v_and_b32_e32 v131, 64, v240
	v_add_f32_e32 v133, v133, v134
	v_xor_b32_e32 v130, 16, v240
	v_add_u32_e32 v131, 64, v131
	v_add_f32_e32 v132, v132, v133
	v_mul_f32_e32 v133, v3, v3
	v_mul_f32_e32 v134, v5, v5
	v_cmp_lt_i32_e32 vcc, v130, v131
	v_fmac_f32_e32 v133, v2, v2
	v_fmac_f32_e32 v134, v4, v4
	v_cndmask_b32_e32 v130, v240, v130, vcc
	v_add_f32_e32 v133, v133, v134
	v_lshlrev_b32_e32 v130, 2, v130
	v_add_f32_e32 v133, v132, v133
	ds_bpermute_b32 v134, v130, v133
	v_xor_b32_e32 v132, 32, v240
	v_cmp_lt_i32_e32 vcc, v132, v131
	s_lshl_b32 s4, s38, 2
	v_and_b32_e32 v0, 63, v153
	v_cndmask_b32_e32 v131, v240, v132, vcc
	v_lshlrev_b32_e32 v132, 2, v131
	s_waitcnt lgkmcnt(0)
	v_add_f32_e32 v133, v133, v134
	ds_bpermute_b32 v134, v132, v133
	s_add_i32 s4, s4, 0
	v_cmp_gt_u32_e32 vcc, 16, v0
	v_lshl_add_u32 v131, v152, 4, s4
	s_and_saveexec_b64 s[4:5], vcc
	s_cbranch_execz .LBB0_390
	s_waitcnt lgkmcnt(0)
	v_add_f32_e32 v133, v133, v134
	ds_write_b32 v131, v133

;     __device__ __forceinline__ void fused(f32x4 (&acc)[2][2][4][2], const Unit& u, int wr, int wc, int fr, int fq, PG8_LAS unsigned char* lds, int wid, int lane) const {
;         const int row0 = u.pm * BM + wr * 64 + fr, col0 = u.pn * BM + wc * 32 + 4 * fq; const int bo = (u.pm >= 32 ? 9216 : 0); const float* gp = gate + bo + col0;
;         f32x4 gv[2][2];
; #pragma unroll
;         for (int bj = 0; bj < 2; ++bj)
; #pragma unroll
;             for (int n = 0; n < 2; ++n) gv[bj][n] = *(const f32x4*)(gp + bj * HALF + n * 16) * coef;
; #pragma unroll
;         for (int ai = 0; ai < 2; ++ai)
; #pragma unroll
;             for (int m = 0; m < 4; ++m) { const size_t off = (size_t)(row0 + ai * HALF + m * 16) * 1024 + col0;
; #pragma unroll
;                 for (int bj = 0; bj < 2; ++bj)
; #pragma unroll
;                     for (int n = 0; n < 2; ++n) { const f32x4 bs = *(const f32x4*)(base + off + bj * HALF + n * 16); acc[ai][bj][m][n] = bs + gv[bj][n] * acc[ai][bj][m][n]; *(f32x4*)(out + off + bj * HALF + n * 16) = acc[ai][bj][m][n]; }
;     ...
;             for (int m = 0; m < 4; ++m) { float q = 0.f;
; #pragma unroll
;                 for (int bj = 0; bj < 2; ++bj)
; #pragma unroll
;                     for (int n = 0; n < 2; ++n) { const f32x4 x = acc[ai][bj][m][n]; q += (x[0] * x[0] + x[1] * x[1]) + (x[2] * x[2] + x[3] * x[3]); }
.LBB0_1157:
	v_readlane_b32 s0, v255, 21
	v_readlane_b32 s1, v255, 22
	s_lshl_b64 s[4:5], s[0:1], 2
	s_add_u32 s1, s8, s4
	s_addc_u32 s18, s9, s5
	s_lshl_b32 s0, s12, 8
	s_lshl_b32 s4, s13, 5
	s_add_i32 s6, s0, s45
	s_lshl_b32 s5, s14, 8
	s_or_b32 s4, s5, s4
	v_lshrrev_b32_e32 v0, 2, v173
	v_or_b32_e32 v186, s6, v142
	v_and_or_b32 v162, v0, 12, s4
	s_cmp_gt_i32 s12, 31
	v_ashrrev_i32_e32 v187, 31, v186
	s_cselect_b32 s4, 0x2400, 0
	v_ashrrev_i32_e32 v163, 31, v162
	v_lshlrev_b64 v[142:143], 12, v[186:187]
	s_lshl_b32 s19, s4, 2
	v_lshlrev_b64 v[164:165], 2, v[162:163]
	v_lshl_add_u64 v[142:143], s[16:17], 0, v[142:143]
	s_add_u32 s4, s1, s19
	v_lshl_add_u64 v[166:167], v[142:143], 0, v[164:165]
	v_or_b32_e32 v142, 16, v186
	s_addc_u32 s5, s18, 0
	v_ashrrev_i32_e32 v143, 31, v142
	v_lshl_add_u64 v[144:145], s[4:5], 0, v[164:165]
	s_mov_b64 s[4:5], 0x5000
	v_lshlrev_b64 v[142:143], 12, v[142:143]
	v_lshl_add_u64 v[134:135], v[144:145], 0, s[4:5]
	v_lshl_add_u64 v[142:143], s[16:17], 0, v[142:143]
	s_movk_i32 s4, 0x5000
	v_lshl_add_u64 v[188:189], v[142:143], 0, v[164:165]
	v_add_co_u32_e32 v142, vcc, s4, v144
	s_barrier
	s_nop 0
	v_addc_co_u32_e32 v143, vcc, 0, v145, vcc
	global_load_dwordx4 v[138:141], v[134:135], off offset:64
	global_load_dwordx4 v[130:133], v[134:135], off offset:512
	s_nop 0
	global_load_dwordx4 v[134:137], v[134:135], off offset:576
	s_nop 0
	global_load_dwordx4 v[146:149], v[166:167], off offset:64
	global_load_dwordx4 v[150:153], v[166:167], off offset:512
	global_load_dwordx4 v[154:157], v[166:167], off offset:576
	global_load_dwordx4 v[158:161], v[188:189], off offset:64
	global_load_dwordx4 v[168:171], v[188:189], off offset:512
	global_load_dwordx4 v[174:177], v[188:189], off offset:576
	s_nop 0
	global_load_dwordx4 v[142:145], v[142:143], off
	s_nop 0
	global_load_dwordx4 v[178:181], v[166:167], off
	global_load_dwordx4 v[182:185], v[188:189], off
	v_or_b32_e32 v190, 32, v186
	v_or_b32_e32 v186, 48, v186
	v_ashrrev_i32_e32 v191, 31, v190
	v_lshlrev_b64 v[190:191], 12, v[190:191]
	v_ashrrev_i32_e32 v187, 31, v186
	v_lshl_add_u64 v[190:191], s[16:17], 0, v[190:191]
	v_lshl_add_u64 v[190:191], v[190:191], 0, v[164:165]
	s_mov_b64 s[4:5], 0x80000
	v_and_b32_e32 v0, 63, v173
	s_waitcnt vmcnt(0)
	v_pk_fma_f32 v[88:89], v[88:89], v[140:141], v[148:149]
	v_pk_fma_f32 v[86:87], v[86:87], v[138:139], v[146:147]
	v_pk_fma_f32 v[24:25], v[24:25], v[132:133], v[152:153]
	v_pk_fma_f32 v[22:23], v[22:23], v[130:131], v[150:151]
	v_pk_fma_f32 v[8:9], v[8:9], v[136:137], v[156:157]
	v_pk_fma_f32 v[6:7], v[6:7], v[134:135], v[154:155]
	v_pk_fma_f32 v[84:85], v[84:85], v[140:141], v[160:161]
	v_pk_fma_f32 v[82:83], v[82:83], v[138:139], v[158:159]
	v_pk_fma_f32 v[20:21], v[20:21], v[132:133], v[170:171]
	v_pk_fma_f32 v[18:19], v[18:19], v[130:131], v[168:169]
	v_pk_fma_f32 v[4:5], v[4:5], v[136:137], v[176:177]
	v_pk_fma_f32 v[2:3], v[2:3], v[134:135], v[174:175]
	v_pk_fma_f32 v[128:129], v[128:129], v[144:145], v[180:181]
	v_pk_fma_f32 v[126:127], v[126:127], v[142:143], v[178:179]
	v_pk_fma_f32 v[116:117], v[116:117], v[144:145], v[184:185]
	v_pk_fma_f32 v[114:115], v[114:115], v[142:143], v[182:183]
	global_store_dwordx4 v[166:167], v[86:89], off offset:64
	global_store_dwordx4 v[166:167], v[22:25], off offset:512
	global_store_dwordx4 v[166:167], v[6:9], off offset:576
	global_store_dwordx4 v[188:189], v[82:85], off offset:64
	global_store_dwordx4 v[188:189], v[18:21], off offset:512
	global_store_dwordx4 v[188:189], v[2:5], off offset:576
	global_store_dwordx4 v[166:167], v[126:129], off
	global_store_dwordx4 v[188:189], v[114:117], off
	v_lshlrev_b64 v[146:147], 12, v[186:187]
	v_lshl_add_u64 v[146:147], s[16:17], 0, v[146:147]
	global_load_dwordx4 v[150:153], v[190:191], off nt
	global_load_dwordx4 v[154:157], v[190:191], off offset:64 nt
	v_lshl_add_u64 v[192:193], v[146:147], 0, v[164:165]
	global_load_dwordx4 v[158:161], v[190:191], off offset:512 nt
	global_load_dwordx4 v[168:171], v[190:191], off offset:576 nt
	global_load_dwordx4 v[174:177], v[192:193], off nt
	global_load_dwordx4 v[178:181], v[192:193], off offset:64 nt
	global_load_dwordx4 v[182:185], v[192:193], off offset:512 nt
	global_load_dwordx4 v[186:189], v[192:193], off offset:576 nt
	v_lshl_add_u64 v[146:147], v[166:167], 0, s[4:5]
	s_mov_b32 s4, 0x80000
	v_add_co_u32_e32 v148, vcc, s4, v166
	s_mov_b32 s4, 0x90000
	s_nop 0
	v_addc_co_u32_e32 v149, vcc, 0, v167, vcc
	v_add_co_u32_e32 v194, vcc, s4, v166
	s_mov_b64 s[4:5], 0x90000
	s_nop 0
	v_addc_co_u32_e32 v195, vcc, 0, v167, vcc
	v_lshl_add_u64 v[196:197], v[166:167], 0, s[4:5]
	s_mov_b64 s[4:5], 0xa0000
	v_mul_f32_e32 v200, v127, v127
	v_mul_f32_e32 v201, v129, v129
	v_fmac_f32_e32 v200, v126, v126
	v_fmac_f32_e32 v201, v128, v128
	v_mul_f32_e32 v198, v7, v7
	v_mul_f32_e32 v199, v9, v9
	v_fmac_f32_e32 v198, v6, v6
	v_fmac_f32_e32 v199, v8, v8
	s_waitcnt vmcnt(7)
	v_pk_fma_f32 v[124:125], v[124:125], v[144:145], v[152:153]
	v_pk_fma_f32 v[122:123], v[122:123], v[142:143], v[150:151]
	s_waitcnt vmcnt(6)
	v_pk_fma_f32 v[108:109], v[108:109], v[140:141], v[156:157]
	v_pk_fma_f32 v[106:107], v[106:107], v[138:139], v[154:155]
	s_waitcnt vmcnt(5)
	v_pk_fma_f32 v[40:41], v[40:41], v[132:133], v[160:161]
	v_pk_fma_f32 v[38:39], v[38:39], v[130:131], v[158:159]
	s_waitcnt vmcnt(4)
	v_pk_fma_f32 v[12:13], v[12:13], v[136:137], v[170:171]
	v_pk_fma_f32 v[10:11], v[10:11], v[134:135], v[168:169]
	s_waitcnt vmcnt(3)
	v_pk_fma_f32 v[120:121], v[120:121], v[144:145], v[176:177]
	v_pk_fma_f32 v[118:119], v[118:119], v[142:143], v[174:175]
	s_waitcnt vmcnt(2)
;     __device__ __forceinline__ void fused(f32x4 (&acc)[2][2][4][2], const Unit& u, int wr, int wc, int fr, int fq, PG8_LAS unsigned char* lds, int wid, int lane) const {
;     ...
;             for (int m = 0; m < 4; ++m) { const size_t off = (size_t)(row0 + ai * HALF + m * 16) * 1024 + col0;
; #pragma unroll
;                 for (int bj = 0; bj < 2; ++bj)
; #pragma unroll
;                     for (int n = 0; n < 2; ++n) { const f32x4 bs = *(const f32x4*)(base + off + bj * HALF + n * 16); acc[ai][bj][m][n] = bs + gv[bj][n] * acc[ai][bj][m][n]; *(f32x4*)(out + off + bj * HALF + n * 16) = acc[ai][bj][m][n]; }
;     ...
;             for (int m = 0; m < 4; ++m) { float q = 0.f;
; #pragma unroll
;                 for (int bj = 0; bj < 2; ++bj)
; #pragma unroll
;                     for (int n = 0; n < 2; ++n) { const f32x4 x = acc[ai][bj][m][n]; q += (x[0] * x[0] + x[1] * x[1]) + (x[2] * x[2] + x[3] * x[3]); }
;                 q += __shfl_xor(q, 16); q += __shfl_xor(q, 32);
	v_pk_fma_f32 v[112:113], v[112:113], v[140:141], v[180:181]
	v_pk_fma_f32 v[110:111], v[110:111], v[138:139], v[178:179]
	s_waitcnt vmcnt(1)
	v_pk_fma_f32 v[36:37], v[36:37], v[132:133], v[184:185]
	v_pk_fma_f32 v[34:35], v[34:35], v[130:131], v[182:183]
	s_waitcnt vmcnt(0)
	v_pk_fma_f32 v[16:17], v[16:17], v[136:137], v[188:189]
	v_pk_fma_f32 v[14:15], v[14:15], v[134:135], v[186:187]
	global_store_dwordx4 v[190:191], v[122:125], off
	global_store_dwordx4 v[190:191], v[106:109], off offset:64
	global_store_dwordx4 v[190:191], v[38:41], off offset:512
	global_store_dwordx4 v[190:191], v[10:13], off offset:576
	global_store_dwordx4 v[192:193], v[118:121], off
	global_store_dwordx4 v[192:193], v[110:113], off offset:64
	global_store_dwordx4 v[192:193], v[34:37], off offset:512
	global_store_dwordx4 v[192:193], v[14:17], off offset:576
	global_load_dwordx4 v[150:153], v[148:149], off nt
	global_load_dwordx4 v[154:157], v[146:147], off offset:64 nt
	global_load_dwordx4 v[158:161], v[146:147], off offset:512 nt
	global_load_dwordx4 v[174:177], v[146:147], off offset:576 nt
	global_load_dwordx4 v[178:181], v[194:195], off nt
	global_load_dwordx4 v[182:185], v[196:197], off offset:64 nt
	global_load_dwordx4 v[186:189], v[196:197], off offset:512 nt
	global_load_dwordx4 v[190:193], v[196:197], off offset:576 nt
	v_lshl_add_u64 v[168:169], v[166:167], 0, s[4:5]
	s_mov_b32 s4, 0xa0000
	v_add_co_u32_e32 v170, vcc, s4, v166
	s_mov_b32 s4, 0xb0000
	s_nop 0
	v_addc_co_u32_e32 v171, vcc, 0, v167, vcc
	s_waitcnt vmcnt(7)
	v_pk_fma_f32 v[104:105], v[104:105], v[144:145], v[152:153]
	v_pk_fma_f32 v[102:103], v[102:103], v[142:143], v[150:151]
	s_waitcnt vmcnt(6)
	v_pk_fma_f32 v[100:101], v[100:101], v[140:141], v[156:157]
	v_pk_fma_f32 v[98:99], v[98:99], v[138:139], v[154:155]
	s_waitcnt vmcnt(5)
	v_pk_fma_f32 v[52:53], v[52:53], v[132:133], v[160:161]
	v_pk_fma_f32 v[50:51], v[50:51], v[130:131], v[158:159]
	s_waitcnt vmcnt(4)
	v_pk_fma_f32 v[28:29], v[28:29], v[136:137], v[176:177]
	v_pk_fma_f32 v[26:27], v[26:27], v[134:135], v[174:175]
	s_waitcnt vmcnt(3)
	v_pk_fma_f32 v[96:97], v[96:97], v[144:145], v[180:181]
	v_pk_fma_f32 v[94:95], v[94:95], v[142:143], v[178:179]
	s_waitcnt vmcnt(2)
	v_pk_fma_f32 v[92:93], v[92:93], v[140:141], v[184:185]
	v_pk_fma_f32 v[90:91], v[90:91], v[138:139], v[182:183]
	s_waitcnt vmcnt(1)
	v_pk_fma_f32 v[48:49], v[48:49], v[132:133], v[188:189]
	v_pk_fma_f32 v[46:47], v[46:47], v[130:131], v[186:187]
	s_waitcnt vmcnt(0)
	v_pk_fma_f32 v[32:33], v[32:33], v[136:137], v[192:193]
	v_pk_fma_f32 v[30:31], v[30:31], v[134:135], v[190:191]
	global_store_dwordx4 v[148:149], v[102:105], off
	global_store_dwordx4 v[146:147], v[98:101], off offset:64
	global_store_dwordx4 v[146:147], v[50:53], off offset:512
	global_store_dwordx4 v[146:147], v[26:29], off offset:576
	global_store_dwordx4 v[194:195], v[94:97], off
	global_store_dwordx4 v[196:197], v[90:93], off offset:64
	global_store_dwordx4 v[196:197], v[46:49], off offset:512
	global_store_dwordx4 v[196:197], v[30:33], off offset:576
	v_add_co_u32_e32 v192, vcc, s4, v166
	s_mov_b64 s[4:5], 0xb0000
	s_nop 0
	v_addc_co_u32_e32 v193, vcc, 0, v167, vcc
	v_lshl_add_u64 v[194:195], v[166:167], 0, s[4:5]
	global_load_dwordx4 v[158:161], v[170:171], off nt
	global_load_dwordx4 v[154:157], v[168:169], off offset:64 nt
	global_load_dwordx4 v[150:153], v[168:169], off offset:512 nt
	global_load_dwordx4 v[146:149], v[168:169], off offset:576 nt
	global_load_dwordx4 v[176:179], v[192:193], off nt
	global_load_dwordx4 v[180:183], v[194:195], off offset:64 nt
	global_load_dwordx4 v[184:187], v[194:195], off offset:512 nt
	global_load_dwordx4 v[188:191], v[194:195], off offset:576 nt
	v_mul_f32_e32 v174, v87, v87
	v_mul_f32_e32 v175, v89, v89
	v_mul_f32_e32 v196, v23, v23
	v_mul_f32_e32 v197, v25, v25
	v_and_b32_e32 v167, 64, v240
	v_fmac_f32_e32 v174, v86, v86
	v_fmac_f32_e32 v175, v88, v88
	v_fmac_f32_e32 v196, v22, v22
	v_fmac_f32_e32 v197, v24, v24
	v_xor_b32_e32 v166, 16, v240
	v_add_u32_e32 v167, 64, v167
	v_add_f32_e32 v174, v174, v175
	v_add_f32_e32 v175, v196, v197
	v_add_f32_e32 v197, v200, v201
	v_cmp_lt_i32_e32 vcc, v166, v167
	v_add_f32_e32 v174, v197, v174
	v_add_f32_e32 v196, v198, v199
	v_cndmask_b32_e32 v166, v240, v166, vcc
	v_add_f32_e32 v174, v174, v175
	v_lshlrev_b32_e32 v166, 2, v166
	v_add_f32_e32 v174, v174, v196
	ds_bpermute_b32 v175, v166, v174
	v_xor_b32_e32 v196, 32, v240
	v_cmp_lt_i32_e32 vcc, v196, v167
	s_lshl_b32 s4, s13, 2
	s_add_i32 s4, s4, 0
	v_cndmask_b32_e32 v167, v240, v196, vcc
	v_lshlrev_b32_e32 v167, 2, v167
	s_waitcnt lgkmcnt(0)
	v_add_f32_e32 v174, v174, v175
	ds_bpermute_b32 v175, v167, v174
	v_cmp_gt_u32_e32 vcc, 16, v0
	s_waitcnt vmcnt(7)
	v_pk_fma_f32 v[80:81], v[80:81], v[144:145], v[160:161]
	v_pk_fma_f32 v[78:79], v[78:79], v[142:143], v[158:159]
	s_waitcnt vmcnt(6)
	v_pk_fma_f32 v[76:77], v[76:77], v[140:141], v[156:157]
	v_pk_fma_f32 v[74:75], v[74:75], v[138:139], v[154:155]
	s_waitcnt vmcnt(5)
	v_pk_fma_f32 v[64:65], v[64:65], v[132:133], v[152:153]
	v_pk_fma_f32 v[62:63], v[62:63], v[130:131], v[150:151]
	s_waitcnt vmcnt(4)
	v_pk_fma_f32 v[56:57], v[56:57], v[136:137], v[148:149]
	v_pk_fma_f32 v[54:55], v[54:55], v[134:135], v[146:147]
	s_waitcnt vmcnt(3)
	v_pk_fma_f32 v[72:73], v[72:73], v[144:145], v[178:179]
	v_pk_fma_f32 v[70:71], v[70:71], v[142:143], v[176:177]
	s_waitcnt vmcnt(2)
	v_pk_fma_f32 v[68:69], v[68:69], v[140:141], v[182:183]
	v_pk_fma_f32 v[66:67], v[66:67], v[138:139], v[180:181]
	s_waitcnt vmcnt(1)
	v_pk_fma_f32 v[60:61], v[60:61], v[132:133], v[186:187]
	v_pk_fma_f32 v[58:59], v[58:59], v[130:131], v[184:185]
	s_waitcnt vmcnt(0)
	v_pk_fma_f32 v[44:45], v[44:45], v[136:137], v[190:191]
	v_pk_fma_f32 v[42:43], v[42:43], v[134:135], v[188:189]
	global_store_dwordx4 v[170:171], v[78:81], off
	global_store_dwordx4 v[168:169], v[74:77], off offset:64
	global_store_dwordx4 v[168:169], v[62:65], off offset:512
	global_store_dwordx4 v[168:169], v[54:57], off offset:576
	global_store_dwordx4 v[192:193], v[70:73], off
	global_store_dwordx4 v[194:195], v[66:69], off offset:64
	global_store_dwordx4 v[194:195], v[58:61], off offset:512
	global_store_dwordx4 v[194:195], v[42:45], off offset:576
	v_lshl_add_u32 v130, v172, 4, s4
	s_and_saveexec_b64 s[4:5], vcc
	s_cbranch_execz .LBB0_1159
	s_waitcnt lgkmcnt(0)
	v_add_f32_e32 v131, v174, v175
	ds_write_b32 v130, v131
